# combined: pipelined GEMM epilogues (7 ids), GLA-B LDS read pipelining, attention ILP softmax + staging stores under PV MFMAs, norm2 load-hoisted + write-through norm stores, GEMM loop 128B aligned
# speedup vs baseline: 1.0105x; 1.0105x over previous
.LBB0_19:
	s_mov_b64 s[8:9], 0
	s_movk_i32 s15, 0x80
	s_andn2_b64 vcc, exec, s[28:29]
	s_mov_b64 s[28:29], 0
	s_cbranch_vccnz .LBB0_24
	s_cmpk_gt_i32 s6, 0x7fff
	s_cbranch_scc1 .LBB0_23
	s_load_dwordx2 s[42:43], s[0:1], 0xa0
	s_load_dwordx2 s[40:41], s[0:1], 0xb8
	v_lshlrev_b32_e32 v18, 4, v227
	s_add_u32 s22, s36, 0x3600000
	s_addc_u32 s23, s37, 0
	s_waitcnt lgkmcnt(0)
	global_load_dwordx4 v[2:5], v18, s[42:43]
	global_load_dwordx4 v[6:9], v18, s[42:43] offset:1024
	global_load_dwordx4 v[10:13], v18, s[42:43] offset:2048
	global_load_dwordx4 v[14:17], v18, s[42:43] offset:3072
	s_ashr_i32 s7, s6, 31
	s_lshl_b32 s42, s30, 4
	v_lshlrev_b32_e32 v28, 3, v227
	v_mov_b32_e32 v29, v0
	s_lshl_b64 s[26:27], s[6:7], 11
	v_lshl_add_u64 v[36:37], s[22:23], 0, v[28:29]
	s_add_u32 s22, s22, s26
	s_addc_u32 s23, s23, s27
	s_ashr_i32 s43, s42, 31
	v_mov_b32_e32 v19, v0
	v_lshl_add_u64 v[38:39], s[22:23], 0, v[28:29]
	s_lshl_b64 s[22:23], s[42:43], 11
	s_lshl_b64 s[26:27], s[6:7], 12
	v_lshl_add_u64 v[34:35], s[40:41], 0, v[18:19]
	v_lshlrev_b32_e32 v20, 2, v227
	s_add_u32 s40, s40, s26
	v_or_b32_e32 v22, 0x100, v20
	v_or_b32_e32 v24, 0x200, v20
	v_or_b32_e32 v26, 0x300, v20
	s_addc_u32 s41, s41, s27
	v_lshl_add_u64 v[40:41], s[40:41], 0, v[18:19]
	s_lshl_b64 s[28:29], s[42:43], 12
	v_lshlrev_b32_e32 v1, 2, v20
	v_lshlrev_b32_e32 v42, 2, v22
	v_lshlrev_b32_e32 v43, 2, v24
	v_lshlrev_b32_e32 v44, 2, v26
	s_mov_b32 s7, s6
.Lnorm2_loop:
	global_load_dwordx4 v[30:33], v[40:41], off nt
	global_load_dwordx4 v[26:29], v[40:41], off offset:1024 nt
	global_load_dwordx4 v[22:25], v[40:41], off offset:2048 nt
	global_load_dwordx4 v[18:21], v[40:41], off offset:3072 nt
	s_add_i32 s43, s21, s7
	s_cmp_lt_i32 s43, 0x8000
	s_cselect_b32 s40, s43, s7
	s_ashr_i32 s41, s40, 31
	s_lshl_b64 s[38:39], s[40:41], 12
	v_lshl_add_u64 v[58:59], v[34:35], 0, s[38:39]
	global_load_dwordx4 v[46:49], v[58:59], off nt
	global_load_dwordx4 v[50:53], v[58:59], off offset:1024 nt
	global_load_dwordx4 v[54:57], v[58:59], off offset:2048 nt
	s_nop 0
	global_load_dwordx4 v[58:61], v[58:59], off offset:3072 nt
	s_lshr_b32 s43, s7, 11
	s_mul_i32 s26, s43, 0x1800
	s_ashr_i32 s27, s26, 31
	s_lshl_b64 s[26:27], s[26:27], 2
	s_add_u32 s26, s36, s26
	s_addc_u32 s27, s37, s27
	s_add_u32 s26, s26, 0x3000
	s_addc_u32 s27, s27, 0
	s_add_u32 s38, s26, 0x1000
	s_addc_u32 s39, s27, 0
	s_lshr_b32 s43, s40, 11
	global_load_dwordx4 v[62:65], v1, s[26:27]
	global_load_dwordx4 v[66:69], v1, s[26:27] offset:1024
	global_load_dwordx4 v[70:73], v1, s[26:27] offset:2048
	global_load_dwordx4 v[74:77], v1, s[26:27] offset:3072
	s_mul_i32 s26, s43, 0x1800
	s_ashr_i32 s27, s26, 31
	s_lshl_b64 s[26:27], s[26:27], 2
	global_load_dwordx4 v[78:81], v1, s[38:39]
	global_load_dwordx4 v[82:85], v42, s[38:39]
	global_load_dwordx4 v[86:89], v43, s[38:39]
	global_load_dwordx4 v[90:93], v44, s[38:39]
	s_add_u32 s26, s36, s26
	s_addc_u32 s27, s37, s27
	s_add_u32 s26, s26, 0x3000
	s_addc_u32 s27, s27, 0
	s_add_u32 s38, s26, 0x1000
	s_addc_u32 s39, s27, 0
	global_load_dwordx4 v[94:97], v1, s[26:27]
	global_load_dwordx4 v[98:101], v1, s[26:27] offset:1024
	global_load_dwordx4 v[102:105], v1, s[26:27] offset:2048
	global_load_dwordx4 v[106:109], v1, s[26:27] offset:3072
	global_load_dwordx4 v[110:113], v1, s[38:39]
	global_load_dwordx4 v[114:117], v42, s[38:39]
	global_load_dwordx4 v[118:121], v43, s[38:39]
	global_load_dwordx4 v[122:125], v44, s[38:39]
	s_lshl_b64 s[40:41], s[40:41], 11
	s_add_i32 s7, s7, s42
	v_lshl_add_u64 v[40:41], v[40:41], 0, s[28:29]
	v_lshl_add_u64 v[126:127], v[36:37], 0, s[40:41]
	s_cmpk_gt_i32 s7, 0x7fff
	s_waitcnt vmcnt(23)
	v_mul_f32_e32 v45, v31, v31
	v_mul_f32_e32 v128, v33, v33
	s_waitcnt vmcnt(22)
	v_mul_f32_e32 v129, v27, v27
	v_mul_f32_e32 v130, v29, v29
	s_waitcnt vmcnt(21)
	v_mul_f32_e32 v131, v23, v23
	v_mul_f32_e32 v132, v25, v25
	v_fmac_f32_e32 v45, v30, v30
	v_fmac_f32_e32 v128, v32, v32
	v_fmac_f32_e32 v129, v26, v26
	v_fmac_f32_e32 v130, v28, v28
	s_waitcnt vmcnt(20)
	v_mul_f32_e32 v133, v19, v19
	v_mul_f32_e32 v134, v21, v21
	v_fmac_f32_e32 v131, v22, v22
	v_fmac_f32_e32 v132, v24, v24
	v_add_f32_e32 v45, v45, v128
	v_add_f32_e32 v128, v129, v130
	v_fmac_f32_e32 v133, v18, v18
	v_fmac_f32_e32 v134, v20, v20
	v_add_f32_e32 v129, v131, v132
	v_add_f32_e32 v45, v45, v128
	v_add_f32_e32 v130, v133, v134
	v_add_f32_e32 v45, v45, v129
	v_add_f32_e32 v45, v45, v130
	s_waitcnt vmcnt(19)
	v_mul_f32_e32 v128, v47, v47
	v_mul_f32_e32 v129, v49, v49
	s_waitcnt vmcnt(18)
	v_mul_f32_e32 v130, v51, v51
	v_mul_f32_e32 v131, v53, v53
	v_add_f32_dpp v45, v45, v45 quad_perm:[1,0,3,2] row_mask:0xf bank_mask:0xf bound_ctrl:1
	s_waitcnt vmcnt(17)
	v_mul_f32_e32 v132, v55, v55
	v_mul_f32_e32 v133, v57, v57
	v_fmac_f32_e32 v128, v46, v46
	v_fmac_f32_e32 v129, v48, v48
	v_fmac_f32_e32 v130, v50, v50
	v_fmac_f32_e32 v131, v52, v52
	v_add_f32_dpp v45, v45, v45 quad_perm:[2,3,0,1] row_mask:0xf bank_mask:0xf bound_ctrl:1
	s_waitcnt vmcnt(16)
	v_mul_f32_e32 v134, v59, v59
	v_mul_f32_e32 v135, v61, v61
	v_fmac_f32_e32 v132, v54, v54
	v_fmac_f32_e32 v133, v56, v56
	v_add_f32_e32 v128, v128, v129
	v_add_f32_e32 v129, v130, v131
	v_add_f32_dpp v45, v45, v45 row_half_mirror row_mask:0xf bank_mask:0xf bound_ctrl:1
	v_fmac_f32_e32 v134, v58, v58
	v_fmac_f32_e32 v135, v60, v60
	v_add_f32_e32 v130, v132, v133
	v_add_f32_e32 v128, v128, v129
	v_add_f32_dpp v45, v45, v45 row_mirror row_mask:0xf bank_mask:0xf bound_ctrl:1
	v_add_f32_e32 v131, v134, v135
	v_add_f32_e32 v128, v128, v130
	v_mov_b32_e32 v129, v45
	v_add_f32_e32 v128, v128, v131
	s_nop 0
	v_permlane16_swap_b32_e32 v45, v129
	v_add_f32_e32 v45, v45, v129
	v_add_f32_dpp v128, v128, v128 quad_perm:[1,0,3,2] row_mask:0xf bank_mask:0xf bound_ctrl:1
	v_mov_b32_e32 v129, v45
	s_nop 1
	v_permlane32_swap_b32_e32 v45, v129
	v_add_f32_dpp v128, v128, v128 quad_perm:[2,3,0,1] row_mask:0xf bank_mask:0xf bound_ctrl:1
	v_add_f32_e32 v45, v45, v129
	v_fmamk_f32 v45, v45, 0x3a800000, v207
	v_add_f32_dpp v128, v128, v128 row_half_mirror row_mask:0xf bank_mask:0xf bound_ctrl:1
	s_waitcnt vmcnt(11)
	v_pk_add_f32 v[78:79], v[78:79], 1.0 op_sel_hi:[1,0]
	v_pk_add_f32 v[80:81], v[80:81], 1.0 op_sel_hi:[1,0]
	v_add_f32_dpp v129, v128, v128 row_mirror row_mask:0xf bank_mask:0xf bound_ctrl:1
	v_mov_b32_e32 v130, v129
	s_nop 1
	v_permlane16_swap_b32_e32 v129, v130
	v_rsq_f32_e32 v128, v45
	v_add_f32_e32 v45, v129, v130
	v_mov_b32_e32 v129, v45
	s_nop 1
	v_permlane32_swap_b32_e32 v45, v129
	v_add_f32_e32 v45, v45, v129
	v_pk_mul_f32 v[30:31], v[30:31], v[128:129] op_sel_hi:[1,0]
	v_fmamk_f32 v45, v45, 0x3a800000, v207
	v_pk_mul_f32 v[30:31], v[2:3], v[30:31]
	v_pk_mul_f32 v[32:33], v[32:33], v[128:129] op_sel_hi:[1,0]
	v_pk_mul_f32 v[20:21], v[20:21], v[128:129] op_sel_hi:[1,0]
	v_pk_mul_f32 v[18:19], v[18:19], v[128:129] op_sel_hi:[1,0]
	v_pk_fma_f32 v[30:31], v[78:79], v[30:31], v[62:63]
	v_rsq_f32_e32 v62, v45
	s_waitcnt vmcnt(8)
	v_pk_add_f32 v[92:93], v[92:93], 1.0 op_sel_hi:[1,0]
	v_pk_add_f32 v[90:91], v[90:91], 1.0 op_sel_hi:[1,0]
	v_pk_mul_f32 v[28:29], v[28:29], v[128:129] op_sel_hi:[1,0]
	v_pk_mul_f32 v[26:27], v[26:27], v[128:129] op_sel_hi:[1,0]
	v_pk_mul_f32 v[24:25], v[24:25], v[128:129] op_sel_hi:[1,0]
	v_pk_mul_f32 v[22:23], v[22:23], v[128:129] op_sel_hi:[1,0]
	v_pk_mul_f32 v[32:33], v[4:5], v[32:33]
	v_pk_mul_f32 v[18:19], v[14:15], v[18:19]
	v_pk_mul_f32 v[20:21], v[16:17], v[20:21]
	v_pk_add_f32 v[84:85], v[84:85], 1.0 op_sel_hi:[1,0]
	v_pk_add_f32 v[82:83], v[82:83], 1.0 op_sel_hi:[1,0]
	v_pk_add_f32 v[88:89], v[88:89], 1.0 op_sel_hi:[1,0]
	v_pk_add_f32 v[86:87], v[86:87], 1.0 op_sel_hi:[1,0]
	v_pk_mul_f32 v[26:27], v[6:7], v[26:27]
	v_pk_mul_f32 v[28:29], v[8:9], v[28:29]
	v_pk_mul_f32 v[22:23], v[10:11], v[22:23]
	v_pk_mul_f32 v[24:25], v[12:13], v[24:25]
	v_pk_fma_f32 v[32:33], v[80:81], v[32:33], v[64:65]
	v_pk_fma_f32 v[20:21], v[20:21], v[92:93], v[76:77]
	v_pk_fma_f32 v[18:19], v[18:19], v[90:91], v[74:75]
	v_pk_fma_f32 v[28:29], v[28:29], v[84:85], v[68:69]
	v_pk_fma_f32 v[26:27], v[26:27], v[82:83], v[66:67]
	v_pk_fma_f32 v[24:25], v[24:25], v[88:89], v[72:73]
	v_pk_fma_f32 v[22:23], v[22:23], v[86:87], v[70:71]
	v_cvt_pk_bf16_f32 v30, v30, v31
	v_cvt_pk_bf16_f32 v31, v32, v33
	v_cvt_pk_bf16_f32 v18, v18, v19
	v_cvt_pk_bf16_f32 v19, v20, v21
	v_cvt_pk_bf16_f32 v26, v26, v27
	v_cvt_pk_bf16_f32 v27, v28, v29
	v_cvt_pk_bf16_f32 v22, v22, v23
	v_cvt_pk_bf16_f32 v23, v24, v25
	global_store_dwordx2 v[38:39], v[30:31], off sc1
	global_store_dwordx2 v[38:39], v[26:27], off offset:512 sc1
	global_store_dwordx2 v[38:39], v[22:23], off offset:1024 sc1
	global_store_dwordx2 v[38:39], v[18:19], off offset:1536 sc1
	v_pk_mul_f32 v[18:19], v[48:49], v[62:63] op_sel_hi:[1,0]
	v_pk_mul_f32 v[20:21], v[46:47], v[62:63] op_sel_hi:[1,0]
	s_waitcnt vmcnt(7)
	v_pk_add_f32 v[112:113], v[112:113], 1.0 op_sel_hi:[1,0]
	v_pk_add_f32 v[110:111], v[110:111], 1.0 op_sel_hi:[1,0]
	v_pk_mul_f32 v[22:23], v[52:53], v[62:63] op_sel_hi:[1,0]
	v_pk_mul_f32 v[24:25], v[50:51], v[62:63] op_sel_hi:[1,0]
	v_pk_mul_f32 v[26:27], v[56:57], v[62:63] op_sel_hi:[1,0]
	v_pk_mul_f32 v[28:29], v[54:55], v[62:63] op_sel_hi:[1,0]
	v_pk_mul_f32 v[30:31], v[60:61], v[62:63] op_sel_hi:[1,0]
	v_pk_mul_f32 v[32:33], v[58:59], v[62:63] op_sel_hi:[1,0]
	v_pk_mul_f32 v[20:21], v[2:3], v[20:21]
	v_pk_mul_f32 v[18:19], v[4:5], v[18:19]
	s_waitcnt vmcnt(6)
	v_pk_add_f32 v[116:117], v[116:117], 1.0 op_sel_hi:[1,0]
	v_pk_add_f32 v[114:115], v[114:115], 1.0 op_sel_hi:[1,0]
	s_waitcnt vmcnt(5)
	v_pk_add_f32 v[120:121], v[120:121], 1.0 op_sel_hi:[1,0]
	v_pk_add_f32 v[118:119], v[118:119], 1.0 op_sel_hi:[1,0]
	s_waitcnt vmcnt(4)
	v_pk_add_f32 v[124:125], v[124:125], 1.0 op_sel_hi:[1,0]
	v_pk_add_f32 v[122:123], v[122:123], 1.0 op_sel_hi:[1,0]
	v_pk_mul_f32 v[24:25], v[6:7], v[24:25]
	v_pk_mul_f32 v[22:23], v[8:9], v[22:23]
	v_pk_mul_f32 v[28:29], v[10:11], v[28:29]
	v_pk_mul_f32 v[26:27], v[12:13], v[26:27]
	v_pk_mul_f32 v[32:33], v[14:15], v[32:33]
	v_pk_mul_f32 v[30:31], v[16:17], v[30:31]
	v_pk_fma_f32 v[18:19], v[18:19], v[112:113], v[96:97]
	v_pk_fma_f32 v[20:21], v[20:21], v[110:111], v[94:95]
	v_lshl_add_u64 v[38:39], v[38:39], 0, s[22:23]
	v_pk_fma_f32 v[22:23], v[22:23], v[116:117], v[100:101]
	v_pk_fma_f32 v[24:25], v[24:25], v[114:115], v[98:99]
	v_pk_fma_f32 v[26:27], v[26:27], v[120:121], v[104:105]
	v_pk_fma_f32 v[28:29], v[28:29], v[118:119], v[102:103]
	v_pk_fma_f32 v[30:31], v[30:31], v[124:125], v[108:109]
	v_pk_fma_f32 v[32:33], v[32:33], v[122:123], v[106:107]
	v_cvt_pk_bf16_f32 v20, v20, v21
	v_cvt_pk_bf16_f32 v21, v18, v19
	v_cvt_pk_bf16_f32 v18, v24, v25
	v_cvt_pk_bf16_f32 v19, v22, v23
	v_cvt_pk_bf16_f32 v22, v28, v29
	v_cvt_pk_bf16_f32 v23, v26, v27
	v_cvt_pk_bf16_f32 v24, v32, v33
	v_cvt_pk_bf16_f32 v25, v30, v31
	global_store_dwordx2 v[126:127], v[20:21], off sc1
	global_store_dwordx2 v[126:127], v[18:19], off offset:512 sc1
	global_store_dwordx2 v[126:127], v[22:23], off offset:1024 sc1
	global_store_dwordx2 v[126:127], v[24:25], off offset:1536 sc1
	s_cbranch_scc0 .Lnorm2_loop

.LBB0_55:
	s_andn2_saveexec_b64 s[54:55], s[54:55]
	ds_write_b128 v197, v[80:83] offset:128
	s_or_b64 exec, exec, s[54:55]
	v_add_f32_e32 v1, v1, v126
	v_fmamk_f32 v1, v1, 0x3c2aaaab, v207
	v_rsq_f32_e32 v1, v1
	ds_write_b128 v198, v[2:5] offset:13312
	s_waitcnt lgkmcnt(0)
	s_barrier
	v_mul_f32_e32 v66, 0x3e16c740, v1
	s_waitcnt lgkmcnt(6)
	v_pk_mul_f32 v[38:39], v[66:67], v[38:39] op_sel_hi:[0,1]
	v_pk_mul_f32 v[38:39], v[38:39], v[110:111]
	v_pk_mul_f32 v[44:45], v[66:67], v[44:45] op_sel_hi:[0,1]
	v_pk_mul_f32 v[44:45], v[44:45], v[86:87]
	v_cvt_pk_bf16_f32 v86, v38, v39
	v_pk_mul_f32 v[38:39], v[66:67], v[106:107] op_sel_hi:[0,1]
	s_waitcnt lgkmcnt(5)
	v_pk_mul_f32 v[30:31], v[38:39], v[30:31]
	v_pk_mul_f32 v[38:39], v[66:67], v[108:109] op_sel_hi:[0,1]
	s_waitcnt lgkmcnt(3)
	v_pk_mul_f32 v[22:23], v[38:39], v[22:23]
	v_pk_mul_f32 v[46:47], v[66:67], v[46:47] op_sel_hi:[0,1]
	s_waitcnt vmcnt(0)
	v_pk_mul_f32 v[38:39], v[22:23], v[34:35]
	v_pk_mul_f32 v[42:43], v[66:67], v[42:43] op_sel_hi:[0,1]
	v_pk_fma_f32 v[38:39], v[30:31], v[26:27], v[38:39] neg_lo:[0,0,1] neg_hi:[0,0,1]
	v_pk_mul_f32 v[30:31], v[30:31], v[34:35]
	v_pk_mul_f32 v[40:41], v[66:67], v[40:41] op_sel_hi:[0,1]
	v_pk_fma_f32 v[22:23], v[22:23], v[26:27], v[30:31]
	v_pk_mul_f32 v[30:31], v[66:67], v[104:105] op_sel_hi:[0,1]
	v_pk_mul_f32 v[26:27], v[66:67], v[102:103] op_sel_hi:[0,1]
	v_pk_mul_f32 v[24:25], v[30:31], v[24:25]
	v_pk_mul_f32 v[26:27], v[26:27], v[32:33]
	v_pk_mul_f32 v[30:31], v[24:25], v[36:37]
	v_pk_mul_f32 v[68:69], v[66:67], v[70:71] op_sel_hi:[0,1]
	v_pk_fma_f32 v[30:31], v[26:27], v[28:29], v[30:31] neg_lo:[0,0,1] neg_hi:[0,0,1]
	v_pk_mul_f32 v[26:27], v[26:27], v[36:37]
	v_pk_mul_f32 v[62:63], v[66:67], v[62:63] op_sel_hi:[0,1]
	v_pk_fma_f32 v[24:25], v[24:25], v[28:29], v[26:27]
	v_pk_mul_f32 v[26:27], v[66:67], v[78:79] op_sel_hi:[0,1]
	v_pk_mul_f32 v[14:15], v[26:27], v[14:15]
	v_pk_mul_f32 v[26:27], v[66:67], v[100:101] op_sel_hi:[0,1]
	s_waitcnt lgkmcnt(2)
	v_pk_mul_f32 v[10:11], v[26:27], v[10:11]
	v_pk_mul_f32 v[70:71], v[66:67], v[72:73] op_sel_hi:[0,1]
	v_pk_mul_f32 v[26:27], v[10:11], v[18:19]
	v_pk_mul_f32 v[64:65], v[66:67], v[64:65] op_sel_hi:[0,1]
	v_pk_fma_f32 v[26:27], v[14:15], v[6:7], v[26:27] neg_lo:[0,0,1] neg_hi:[0,0,1]
	v_pk_mul_f32 v[14:15], v[14:15], v[18:19]
	v_pk_mul_f32 v[58:59], v[66:67], v[58:59] op_sel_hi:[0,1]
	v_pk_fma_f32 v[6:7], v[10:11], v[6:7], v[14:15]
	v_pk_mul_f32 v[14:15], v[66:67], v[76:77] op_sel_hi:[0,1]
	v_pk_mul_f32 v[10:11], v[66:67], v[74:75] op_sel_hi:[0,1]
	v_pk_mul_f32 v[12:13], v[14:15], v[12:13]
	v_pk_mul_f32 v[10:11], v[10:11], v[16:17]
	v_pk_mul_f32 v[14:15], v[12:13], v[20:21]
	v_pk_mul_f32 v[54:55], v[66:67], v[54:55] op_sel_hi:[0,1]
	v_pk_fma_f32 v[14:15], v[10:11], v[8:9], v[14:15] neg_lo:[0,0,1] neg_hi:[0,0,1]
	v_pk_mul_f32 v[10:11], v[10:11], v[20:21]
	v_pk_mul_f32 v[60:61], v[66:67], v[60:61] op_sel_hi:[0,1]
	v_pk_mul_f32 v[56:57], v[66:67], v[56:57] op_sel_hi:[0,1]
	v_pk_mul_f32 v[50:51], v[66:67], v[50:51] op_sel_hi:[0,1]
	v_pk_mul_f32 v[46:47], v[46:47], v[114:115]
	v_pk_mul_f32 v[52:53], v[66:67], v[52:53] op_sel_hi:[0,1]
	v_pk_mul_f32 v[48:49], v[66:67], v[48:49] op_sel_hi:[0,1]
	v_pk_mul_f32 v[42:43], v[42:43], v[112:113]
	v_pk_mul_f32 v[40:41], v[40:41], v[84:85]
	v_pk_fma_f32 v[8:9], v[12:13], v[8:9], v[10:11]
	v_cvt_pk_bf16_f32 v103, v14, v15
	v_mov_b32_e32 v14, v0
	v_mov_b32_e32 v15, v0
	v_pk_mul_f32 v[68:69], v[68:69], v[124:125]
	v_pk_mul_f32 v[62:63], v[62:63], v[122:123]
	v_pk_mul_f32 v[70:71], v[70:71], v[90:91]
	v_pk_mul_f32 v[64:65], v[64:65], v[88:89]
	v_pk_mul_f32 v[58:59], v[58:59], v[120:121]
	v_pk_mul_f32 v[54:55], v[54:55], v[118:119]
	v_pk_mul_f32 v[60:61], v[60:61], v[94:95]
	v_pk_mul_f32 v[56:57], v[56:57], v[92:93]
	v_pk_mul_f32 v[50:51], v[50:51], v[116:117]
	v_pk_mul_f32 v[52:53], v[52:53], v[98:99]
	v_pk_mul_f32 v[48:49], v[48:49], v[96:97]
	v_cvt_pk_bf16_f32 v98, v46, v47
	v_cvt_pk_bf16_f32 v84, v42, v43
	v_cvt_pk_bf16_f32 v85, v44, v45
	v_cvt_pk_bf16_f32 v87, v40, v41
	v_cvt_pk_bf16_f32 v100, v38, v39
	v_cvt_pk_bf16_f32 v101, v30, v31
	v_cvt_pk_bf16_f32 v102, v26, v27
	v_cvt_pk_bf16_f32 v104, v22, v23
	v_cvt_pk_bf16_f32 v105, v24, v25
	v_cvt_pk_bf16_f32 v106, v6, v7
	v_cvt_pk_bf16_f32 v107, v8, v9
	s_lshl_b32 s48, s38, 2
	v_mov_b32_e32 v1, v0
	v_mov_b32_e32 v2, v0
	v_mov_b32_e32 v3, v0
	v_mov_b32_e32 v4, v0
	v_mov_b32_e32 v5, v0
	v_mov_b32_e32 v6, v0
	v_mov_b32_e32 v7, v0
	v_mov_b32_e32 v8, v0
	v_mov_b32_e32 v9, v0
	v_mov_b32_e32 v10, v0
	v_mov_b32_e32 v11, v0
	v_mov_b32_e32 v12, v0
	v_mov_b32_e32 v13, v0
	v_mov_b64_e32 v[30:31], v[14:15]
	v_mov_b64_e32 v[46:47], v[14:15]
	v_cvt_pk_bf16_f32 v88, v68, v69
	v_cvt_pk_bf16_f32 v89, v70, v71
	v_cvt_pk_bf16_f32 v90, v62, v63
	v_cvt_pk_bf16_f32 v91, v64, v65
	v_cvt_pk_bf16_f32 v92, v58, v59
	v_cvt_pk_bf16_f32 v93, v60, v61
	v_cvt_pk_bf16_f32 v94, v54, v55
	v_cvt_pk_bf16_f32 v95, v56, v57
	v_cvt_pk_bf16_f32 v96, v50, v51
	v_cvt_pk_bf16_f32 v97, v52, v53
	v_cvt_pk_bf16_f32 v99, v48, v49
	s_add_i32 s48, s48, s26
	s_mov_b32 s49, 0
	v_mov_b32_e32 v151, 0
	v_mov_b64_e32 v[174:175], v[172:173]
	v_mov_b32_e32 v176, v228
	v_mov_b32_e32 v178, v205
	v_mov_b32_e32 v180, v204
	v_mov_b64_e32 v[182:183], v[146:147]
	v_mov_b64_e32 v[28:29], v[12:13]
	v_mov_b64_e32 v[26:27], v[10:11]
	v_mov_b64_e32 v[24:25], v[8:9]
	v_mov_b64_e32 v[22:23], v[6:7]
	v_mov_b64_e32 v[20:21], v[4:5]
	v_mov_b64_e32 v[18:19], v[2:3]
	v_mov_b64_e32 v[16:17], v[0:1]
	v_mov_b64_e32 v[44:45], v[12:13]
	v_mov_b64_e32 v[42:43], v[10:11]
	v_mov_b64_e32 v[40:41], v[8:9]
	v_mov_b64_e32 v[38:39], v[6:7]
	v_mov_b64_e32 v[36:37], v[4:5]
	v_mov_b64_e32 v[34:35], v[2:3]
	v_mov_b64_e32 v[32:33], v[0:1]
	global_load_dwordx4 v[2:5], v[182:183], off
	s_cmp_lg_u64 s[42:43], 0
	s_cbranch_scc1 .Latt_L_hi_1
	v_ashrrev_i32_e32 v177, 31, v176
	v_lshlrev_b64 v[6:7], 6, v[176:177]
	v_lshl_add_u64 v[6:7], v[144:145], 0, v[6:7]
	global_load_dwordx4 v[80:83], v[6:7], off
	s_branch .Latt_L_v_1
.Latt_L_hi_1:
	s_cmp_lg_u64 s[44:45], 0
	s_cbranch_scc0 .Latt_L_v_1
	v_ashrrev_i32_e32 v181, 31, v180
	v_lshl_add_u64 v[6:7], v[180:181], 2, s[8:9]
	v_ashrrev_i32_e32 v179, 31, v178
	global_load_dword v153, v[6:7], off
	v_lshl_add_u64 v[6:7], v[178:179], 2, s[22:23]
	global_load_dword v155, v[6:7], off
.Latt_L_v_1:
	global_load_dwordx4 v[6:9], v[174:175], off
	v_lshl_add_u64 v[182:183], v[182:183], 0, s[10:11]
	v_add_u32_e32 v180, 0x400, v180
	v_add_u32_e32 v178, 64, v178
	v_add_u32_e32 v176, 64, v176
	v_lshl_add_u64 v[174:175], v[174:175], 0, s[12:13]
.Latt_u_loop:
	s_cmp_gt_i32 s49, s48
	s_cbranch_scc1 .Latt_u_skipC
	s_bitcmp1_b32 s49, 0
	s_cselect_b32 s53, 0x5900, 0
	s_add_i32 s53, s53, 0
	v_add3_u32 v1, s53, v190, v191
	ds_read_b128 v[10:13], v1
	ds_read_b128 v[108:111], v1 offset:32
	ds_read_b128 v[48:51], v1 offset:6656
	ds_read_b128 v[112:115], v1 offset:64
	ds_read_b128 v[116:119], v1 offset:6688
	ds_read_b128 v[120:123], v1 offset:6720
	s_waitcnt lgkmcnt(5)
	v_mfma_f32_32x32x16_bf16 v[64:79], v[10:13], v[88:91], 0
	ds_read_b128 v[230:233], v1 offset:6752
	ds_read_b128 v[234:237], v1 offset:96
	ds_read_b128 v[238:241], v1 offset:128
	ds_read_b128 v[242:245], v1 offset:6784
	ds_read_b128 v[246:249], v1 offset:160
	ds_read_b128 v[250:253], v1 offset:6816
	s_waitcnt lgkmcnt(9)
	v_mfma_f32_32x32x16_bf16 v[48:63], v[48:51], v[88:91], 0
	v_mfma_f32_32x32x16_bf16 v[64:79], v[108:111], v[92:95], v[64:79]
	s_waitcnt lgkmcnt(7)
	v_mfma_f32_32x32x16_bf16 v[48:63], v[116:119], v[92:95], v[48:63]
	v_mfma_f32_32x32x16_bf16 v[64:79], v[112:115], v[96:99], v[64:79]
	s_waitcnt lgkmcnt(6)
	v_mfma_f32_32x32x16_bf16 v[48:63], v[120:123], v[96:99], v[48:63]
	s_waitcnt lgkmcnt(4)
	v_mfma_f32_32x32x16_bf16 v[64:79], v[234:237], v[84:87], v[64:79]
	v_add3_u32 v157, s53, v192, v191
	v_add_u32_e32 v1, s53, v193
	ds_read_b128 v[128:131], v157 offset:13312
	ds_read_b128 v[124:127], v157 offset:13344
	ds_read_b128 v[120:123], v157 offset:17952
	ds_read_b128 v[116:119], v157 offset:13376
	ds_read_b128 v[112:115], v157 offset:17984
	ds_read_b128 v[108:111], v157 offset:13408
	ds_read_b128 v[10:13], v157 offset:18016
	v_mfma_f32_32x32x16_bf16 v[48:63], v[230:233], v[84:87], v[48:63]
	s_waitcnt lgkmcnt(10)
	v_mfma_f32_32x32x16_bf16 v[64:79], v[238:241], v[100:103], v[64:79]
	s_waitcnt lgkmcnt(9)
	v_mfma_f32_32x32x16_bf16 v[48:63], v[242:245], v[100:103], v[48:63]
	s_waitcnt lgkmcnt(8)
	v_mfma_f32_32x32x16_bf16 v[64:79], v[246:249], v[104:107], v[64:79]
	s_waitcnt lgkmcnt(7)
	v_mfma_f32_32x32x16_bf16 v[48:63], v[250:253], v[104:107], v[48:63]
	ds_read_b128 v[230:233], v1 offset:22528
	ds_read_b128 v[234:237], v1 offset:22544
	ds_read_b128 v[238:241], v1 offset:22592
	ds_read_b128 v[242:245], v1 offset:22608
	ds_read_b128 v[246:249], v1 offset:22656
	ds_read_b128 v[250:253], v1 offset:22672
	ds_read_b128 v[210:213], v1 offset:22720
	ds_read_b128 v[214:217], v1 offset:22736
	s_waitcnt lgkmcnt(4)
	s_nop 1
	v_fma_f32 v64, v64, v230, -v165
	v_fma_f32 v65, v65, v231, -v165
	v_fma_f32 v66, v66, v232, -v165
	v_fma_f32 v67, v67, v233, -v165
	v_fma_f32 v68, v68, v234, -v165
	v_fma_f32 v69, v69, v235, -v165
	v_fma_f32 v70, v70, v236, -v165
	v_fma_f32 v71, v71, v237, -v165
	v_fma_f32 v72, v72, v238, -v165
	v_fma_f32 v73, v73, v239, -v165
	v_fma_f32 v74, v74, v240, -v165
	v_fma_f32 v75, v75, v241, -v165
	v_fma_f32 v76, v76, v242, -v165
	v_fma_f32 v77, v77, v243, -v165
	v_fma_f32 v78, v78, v244, -v165
	v_fma_f32 v79, v79, v245, -v165
	ds_read_b128 v[230:233], v157 offset:17920
	s_waitcnt lgkmcnt(1)
	v_fma_f32 v48, v48, v246, -v165
	v_fma_f32 v49, v49, v247, -v165
	v_fma_f32 v50, v50, v248, -v165
	v_fma_f32 v51, v51, v249, -v165
	v_fma_f32 v52, v52, v250, -v165
	v_fma_f32 v53, v53, v251, -v165
	v_fma_f32 v54, v54, v252, -v165
	v_fma_f32 v55, v55, v253, -v165
	v_fma_f32 v56, v56, v210, -v165
	v_fma_f32 v57, v57, v211, -v165
	v_fma_f32 v58, v58, v212, -v165
	v_fma_f32 v59, v59, v213, -v165
	v_fma_f32 v60, v60, v214, -v165
	v_fma_f32 v61, v61, v215, -v165
	v_fma_f32 v62, v62, v216, -v165
	v_fma_f32 v63, v63, v217, -v165
	v_exp_f32_e32 v64, v64
	v_exp_f32_e32 v65, v65
	v_exp_f32_e32 v66, v66
	v_exp_f32_e32 v67, v67
	v_exp_f32_e32 v68, v68
	v_exp_f32_e32 v69, v69
	v_exp_f32_e32 v70, v70
	v_exp_f32_e32 v71, v71
	v_exp_f32_e32 v72, v72
	v_exp_f32_e32 v73, v73
	v_exp_f32_e32 v74, v74
	v_exp_f32_e32 v75, v75
	v_exp_f32_e32 v76, v76
	v_exp_f32_e32 v77, v77
	v_exp_f32_e32 v78, v78
	v_exp_f32_e32 v79, v79
	v_exp_f32_e32 v48, v48
	v_exp_f32_e32 v49, v49
	v_exp_f32_e32 v50, v50
	v_exp_f32_e32 v51, v51
	v_exp_f32_e32 v52, v52
	v_exp_f32_e32 v53, v53
	v_exp_f32_e32 v54, v54
	v_exp_f32_e32 v55, v55
	v_exp_f32_e32 v56, v56
	v_exp_f32_e32 v57, v57
	v_exp_f32_e32 v58, v58
	v_exp_f32_e32 v59, v59
	v_exp_f32_e32 v60, v60
	v_exp_f32_e32 v61, v61
	v_exp_f32_e32 v62, v62
	v_exp_f32_e32 v63, v63
	v_add_f32_e32 v234, v64, v48
	v_add_f32_e32 v235, v65, v49
	v_add_f32_e32 v236, v66, v50
	v_add_f32_e32 v237, v67, v51
	v_add_f32_e32 v238, v68, v52
	v_add_f32_e32 v239, v69, v53
	v_add_f32_e32 v240, v70, v54
	v_add_f32_e32 v241, v71, v55
	v_add_f32_e32 v242, v72, v56
	v_add_f32_e32 v243, v73, v57
	v_add_f32_e32 v244, v74, v58
	v_add_f32_e32 v245, v75, v59
	v_add_f32_e32 v246, v76, v60
	v_add_f32_e32 v247, v77, v61
	v_add_f32_e32 v248, v78, v62
	v_add_f32_e32 v249, v79, v63
	v_add_f32_e32 v234, v234, v235
	v_add_f32_e32 v236, v236, v237
	v_add_f32_e32 v238, v238, v239
	v_add_f32_e32 v240, v240, v241
	v_add_f32_e32 v242, v242, v243
	v_add_f32_e32 v244, v244, v245
	v_add_f32_e32 v246, v246, v247
	v_add_f32_e32 v248, v248, v249
	v_add_f32_e32 v234, v234, v236
	v_add_f32_e32 v238, v238, v240
	v_add_f32_e32 v242, v242, v244
	v_add_f32_e32 v246, v246, v248
	v_add_f32_e32 v234, v234, v238
	v_add_f32_e32 v242, v242, v246
	v_add_f32_e32 v234, v234, v242
	v_cvt_pk_bf16_f32 v64, v64, v65
	v_cvt_pk_bf16_f32 v65, v66, v67
	v_cvt_pk_bf16_f32 v66, v68, v69
	v_cvt_pk_bf16_f32 v67, v70, v71
	v_cvt_pk_bf16_f32 v68, v72, v73
	v_cvt_pk_bf16_f32 v69, v74, v75
	v_cvt_pk_bf16_f32 v70, v76, v77
	v_cvt_pk_bf16_f32 v71, v78, v79
	v_cvt_pk_bf16_f32 v48, v48, v49
	v_cvt_pk_bf16_f32 v49, v50, v51
	v_cvt_pk_bf16_f32 v50, v52, v53
	v_cvt_pk_bf16_f32 v51, v54, v55
	v_cvt_pk_bf16_f32 v52, v56, v57
	v_cvt_pk_bf16_f32 v53, v58, v59
	v_cvt_pk_bf16_f32 v54, v60, v61
	v_cvt_pk_bf16_f32 v55, v62, v63
	v_add_f32_e32 v151, v151, v234
	s_cmp_ge_u32 s49, s47
	s_cbranch_scc1 .Latt_u_pvplain
	v_mfma_f32_32x32x16_bf16 v[32:47], v[128:131], v[64:67], v[32:47]
	s_waitcnt lgkmcnt(0)
	v_mfma_f32_32x32x16_bf16 v[16:31], v[230:233], v[64:67], v[16:31]
	s_bitcmp0_b32 s49, 0
	s_cselect_b32 s53, 0x5900, 0
	v_add3_u32 v1, s53, v143, v134
	s_waitcnt vmcnt(1)
	ds_write_b128 v1, v[2:5]
	v_mfma_f32_32x32x16_bf16 v[32:47], v[124:127], v[68:71], v[32:47]
	v_mfma_f32_32x32x16_bf16 v[16:31], v[120:123], v[68:71], v[16:31]
	s_cmp_lg_u64 s[42:43], 0
	s_cbranch_scc1 .Latt_S_hi_3
	v_add3_u32 v1, s53, v188, v142
	ds_write_b128 v1, v[80:83] offset:128
	s_branch .Latt_S_v_3
.Latt_S_hi_3:
	s_cmp_lg_u64 s[44:45], 0
	s_cbranch_scc0 .Latt_S_v_3
	v_add_f32_e32 v1, v153, v155
	v_fmamk_f32 v1, v1, 0x3c2aaaab, v207
	v_rsq_f32_e32 v1, v1
	v_add_u32_e32 v2, s53, v187
	ds_write_b32 v2, v1 offset:21504
.Latt_S_v_3:
	v_mfma_f32_32x32x16_bf16 v[32:47], v[116:119], v[48:51], v[32:47]
	v_mfma_f32_32x32x16_bf16 v[16:31], v[112:115], v[48:51], v[16:31]
	v_add3_u32 v1, s53, v189, v134
	s_waitcnt vmcnt(0)
	ds_write_b128 v1, v[6:9] offset:13312
	v_mfma_f32_32x32x16_bf16 v[32:47], v[108:111], v[52:55], v[32:47]
	v_mfma_f32_32x32x16_bf16 v[16:31], v[10:13], v[52:55], v[16:31]
	s_waitcnt lgkmcnt(0)
	s_branch .Latt_u_afterS
.Latt_u_pvplain:
	v_mfma_f32_32x32x16_bf16 v[32:47], v[128:131], v[64:67], v[32:47]
	s_waitcnt lgkmcnt(0)
	v_mfma_f32_32x32x16_bf16 v[16:31], v[230:233], v[64:67], v[16:31]
	v_mfma_f32_32x32x16_bf16 v[32:47], v[124:127], v[68:71], v[32:47]
	v_mfma_f32_32x32x16_bf16 v[16:31], v[120:123], v[68:71], v[16:31]
	v_mfma_f32_32x32x16_bf16 v[32:47], v[116:119], v[48:51], v[32:47]
	v_mfma_f32_32x32x16_bf16 v[16:31], v[112:115], v[48:51], v[16:31]
	v_mfma_f32_32x32x16_bf16 v[32:47], v[108:111], v[52:55], v[32:47]
	v_mfma_f32_32x32x16_bf16 v[16:31], v[10:13], v[52:55], v[16:31]
	s_branch .Latt_u_noS
.Latt_u_skipC:
	s_cmp_ge_u32 s49, s47
	s_cbranch_scc1 .Latt_u_noS
	s_bitcmp0_b32 s49, 0
	s_cselect_b32 s53, 0x5900, 0
	v_add3_u32 v1, s53, v143, v134
	s_waitcnt vmcnt(1)
	ds_write_b128 v1, v[2:5]
	s_cmp_lg_u64 s[42:43], 0
	s_cbranch_scc1 .Latt_S_hi_5
	v_add3_u32 v1, s53, v188, v142
	ds_write_b128 v1, v[80:83] offset:128
	s_branch .Latt_S_v_5

.Latt_S_v_5:
	v_add3_u32 v1, s53, v189, v134
	s_waitcnt vmcnt(0)
	ds_write_b128 v1, v[6:9] offset:13312
	s_waitcnt lgkmcnt(0)
.Latt_u_afterS:
	s_add_i32 s53, s49, 2
	s_cmp_gt_u32 s53, s47
	s_cbranch_scc1 .Latt_u_noS
	global_load_dwordx4 v[2:5], v[182:183], off
	s_cmp_lg_u64 s[42:43], 0
	s_cbranch_scc1 .Latt_L_hi_6
	v_ashrrev_i32_e32 v177, 31, v176
	v_lshlrev_b64 v[6:7], 6, v[176:177]
	v_lshl_add_u64 v[6:7], v[144:145], 0, v[6:7]
	global_load_dwordx4 v[80:83], v[6:7], off
	s_branch .Latt_L_v_6

.Latt_u_noS:
	s_add_i32 s49, s49, 1
	s_cmp_gt_u32 s49, s47
	s_cbranch_scc1 .LBB0_44
	s_barrier
	s_branch .Latt_u_loop
	s_nop 0
	s_nop 0
	s_nop 0
	s_nop 0
	s_nop 0
	s_nop 0
	s_nop 0
	s_nop 0
	s_nop 0
	s_nop 0
	s_nop 0
	s_nop 0
	s_nop 0
	s_nop 0
	s_nop 0
	s_nop 0
	s_nop 0
	s_nop 0
	s_nop 0
	s_nop 0
	s_nop 0
	s_nop 0
	s_nop 0
	s_nop 0
	s_nop 0
	s_nop 0
	s_nop 0
	s_nop 0
	s_nop 0
	s_nop 0
	s_nop 0
	s_nop 0
	s_nop 0
	s_nop 0
	s_nop 0
	s_nop 0
	s_nop 0
	s_nop 0
	s_nop 0
	s_nop 0
	s_nop 0
	s_nop 0
	s_nop 0
	s_nop 0
	s_nop 0
	s_nop 0
	s_nop 0
	s_nop 0
	s_nop 0
	s_nop 0
	s_nop 0
	s_nop 0
	s_nop 0
	s_nop 0
	s_nop 0
	s_nop 0
	s_nop 0
	s_nop 0
	s_nop 0
	s_nop 0
	s_nop 0
	s_nop 0
	s_nop 0
	s_nop 0
	s_nop 0
	s_nop 0
	s_nop 0
	s_nop 0
	s_nop 0
	s_nop 0
	s_nop 0
	s_nop 0
	s_nop 0
	s_nop 0
	s_nop 0
	s_nop 0
	s_nop 0
	s_nop 0
	s_nop 0
	s_nop 0
	s_nop 0
	s_nop 0
	s_nop 0
	s_nop 0
	s_nop 0
	s_nop 0
	s_nop 0
	s_nop 0
	s_nop 0
	s_nop 0
	s_nop 0
	s_nop 0
	s_nop 0
	s_nop 0
	s_nop 0
	s_nop 0
	s_nop 0
	s_nop 0
	s_nop 0
	s_nop 0
	s_nop 0
	s_nop 0
	s_nop 0
	s_nop 0
	s_nop 0
	s_nop 0
	s_nop 0
	s_nop 0
	s_nop 0
	s_nop 0
	s_nop 0
	s_nop 0
	s_nop 0
	s_nop 0
	s_nop 0
	s_nop 0
	s_nop 0
	s_nop 0
	s_nop 0
	s_nop 0
	s_nop 0
	s_nop 0
	s_nop 0
	s_nop 0
	s_nop 0
	s_nop 0
	s_nop 0
	s_nop 0
	s_nop 0
	s_nop 0
	s_nop 0
	s_nop 0
	s_nop 0
	s_nop 0
	s_nop 0
	s_nop 0
	s_nop 0
	s_nop 0
	s_nop 0
	s_nop 0
	s_nop 0
	s_nop 0
	s_nop 0
	s_nop 0
	s_nop 0
	s_nop 0
	s_nop 0
	s_nop 0
	s_nop 0
	s_nop 0
	s_nop 0
	s_nop 0
	s_nop 0
	s_nop 0
	s_nop 0
	s_nop 0
	s_nop 0
	s_nop 0
	s_nop 0
	s_nop 0
	s_nop 0
	s_nop 0
	s_nop 0
	s_nop 0
	s_nop 0
	s_nop 0
	s_nop 0
	s_nop 0
	s_nop 0
	s_nop 0
	s_nop 0
	s_nop 0
	s_nop 0
	s_nop 0
	s_nop 0
	s_nop 0
	s_nop 0
	s_nop 0
	s_nop 0
	s_nop 0
	s_nop 0
	s_nop 0
	s_nop 0
	s_nop 0
	s_nop 0
	s_nop 0
	s_nop 0
	s_nop 0
	s_nop 0
	s_nop 0
	s_nop 0
	s_nop 0
	s_nop 0
	s_nop 0
	s_nop 0
	s_nop 0
	s_nop 0
	s_nop 0
	s_nop 0
	s_nop 0
	s_nop 0
	s_nop 0
	s_nop 0
	s_nop 0
	s_nop 0
	s_nop 0
	s_nop 0
	s_nop 0
	s_nop 0
	s_nop 0
	s_nop 0
	s_nop 0
	s_nop 0
	s_nop 0
	s_nop 0
	s_nop 0
	s_nop 0
	s_nop 0
	s_nop 0
	s_nop 0
	s_nop 0
	s_nop 0
	s_nop 0
	s_nop 0
	s_nop 0
	s_nop 0
	s_nop 0
	s_nop 0
	s_nop 0
	s_nop 0
	s_nop 0
	s_nop 0
	s_nop 0
	s_nop 0
	s_nop 0
	s_nop 0
	s_nop 0
	s_nop 0
	s_nop 0
	s_nop 0
	s_nop 0
	s_nop 0
	s_nop 0
	s_nop 0
	s_nop 0
	s_nop 0
	s_nop 0
	s_nop 0
	s_nop 0
	s_nop 0
	s_nop 0
	s_nop 0
	s_nop 0
	s_nop 0
	s_nop 0
	s_nop 0
	s_nop 0
	s_nop 0
	s_nop 0
	s_nop 0
	s_nop 0
	s_nop 0
	s_nop 0
	s_nop 0
	s_nop 0
	s_nop 0
	s_nop 0
	s_nop 0
	s_nop 0
	s_nop 0
	s_nop 0
	s_nop 0
	s_nop 0
	s_nop 0
	s_nop 0
	s_nop 0
	s_nop 0
	s_nop 0
	s_nop 0
	s_nop 0
	s_nop 0
	s_nop 0
	s_nop 0
	s_nop 0
	s_nop 0
	s_nop 0
	s_nop 0
	s_nop 0
	s_nop 0
	s_nop 0
	s_nop 0
	s_nop 0
	s_nop 0
	s_nop 0
	s_nop 0
	s_nop 0
	s_nop 0
	s_nop 0
	s_nop 0
	s_nop 0

.LBB0_115:
	s_add_i32 s44, s55, -2
	v_lshl_add_u64 v[204:205], v[188:189], 0, s[56:57]
	s_and_b32 s61, s44, 1
	v_add_co_u32_e64 v96, s[44:45], s83, v204
	v_lshl_add_u64 v[202:203], v[192:193], 0, s[56:57]
	s_nop 0
	v_addc_co_u32_e64 v97, s[44:45], 0, v205, s[44:45]
	global_load_dwordx4 v[160:163], v[96:97], off
	v_add_co_u32_e64 v96, s[44:45], s83, v202
	v_ashrrev_i32_e32 v197, 31, v196
	s_nop 0
	v_addc_co_u32_e64 v97, s[44:45], 0, v203, s[44:45]
	v_lshlrev_b64 v[200:201], 11, v[196:197]
	v_ashrrev_i32_e32 v195, 31, v194
	global_load_dwordx4 v[156:159], v[96:97], off
	v_lshl_add_u64 v[96:97], v[178:179], 0, v[200:201]
	v_lshlrev_b64 v[198:199], 11, v[194:195]
	s_mul_i32 s62, s61, 0x8e00
	global_load_dwordx4 v[152:155], v[96:97], off
	v_lshl_add_u64 v[96:97], v[178:179], 0, v[198:199]
	global_load_dwordx4 v[148:151], v[96:97], off
	v_add_u32_e32 v96, s62, v233
	ds_read_b128 v[98:101], v96 offset:35840
	ds_read_b128 v[102:105], v96 offset:35872
	ds_read_b128 v[106:109], v96 offset:35904
	ds_read_b128 v[238:241], v96 offset:35936
	v_add_u32_e32 v97, v96, v230
	s_waitcnt lgkmcnt(3)
	v_pk_mul_f32 v[66:67], v[100:101], v[66:67]
	s_waitcnt lgkmcnt(2)
	v_pk_mul_f32 v[68:69], v[102:103], v[68:69]
	s_waitcnt lgkmcnt(1)
	v_pk_mul_f32 v[72:73], v[106:107], v[72:73]
	s_waitcnt lgkmcnt(0)
	v_pk_mul_f32 v[76:77], v[238:239], v[76:77]
	v_pk_mul_f32 v[78:79], v[240:241], v[78:79]
	v_pk_mul_f32 v[74:75], v[108:109], v[74:75]
	v_pk_mul_f32 v[70:71], v[104:105], v[70:71]
	v_pk_mul_f32 v[64:65], v[98:99], v[64:65]
	ds_read_b128 v[98:101], v96 offset:35968
	ds_read_b128 v[102:105], v96 offset:36000
	ds_read_b128 v[106:109], v96 offset:36032
	ds_read_b128 v[238:241], v96 offset:36064
	v_add_u32_e32 v183, v96, v231
	s_waitcnt lgkmcnt(3)
	v_pk_mul_f32 v[50:51], v[100:101], v[50:51]
	s_waitcnt lgkmcnt(2)
	v_pk_mul_f32 v[52:53], v[102:103], v[52:53]
	s_waitcnt lgkmcnt(1)
	v_pk_mul_f32 v[56:57], v[106:107], v[56:57]
	s_waitcnt lgkmcnt(0)
	v_pk_mul_f32 v[60:61], v[238:239], v[60:61]
	v_pk_mul_f32 v[62:63], v[240:241], v[62:63]
	v_pk_mul_f32 v[58:59], v[108:109], v[58:59]
	v_pk_mul_f32 v[54:55], v[104:105], v[54:55]
	v_pk_mul_f32 v[48:49], v[98:99], v[48:49]
	ds_read_b128 v[98:101], v96 offset:36096
	ds_read_b128 v[102:105], v96 offset:36128
	ds_read_b128 v[106:109], v96 offset:36160
	ds_read_b128 v[238:241], v96 offset:36192
	s_lshl_b32 s44, s61, 11
	s_waitcnt lgkmcnt(3)
	v_pk_mul_f32 v[34:35], v[100:101], v[34:35]
	s_waitcnt lgkmcnt(2)
	v_pk_mul_f32 v[36:37], v[102:103], v[36:37]
	s_waitcnt lgkmcnt(1)
	v_pk_mul_f32 v[40:41], v[106:107], v[40:41]
	s_waitcnt lgkmcnt(0)
	v_pk_mul_f32 v[44:45], v[238:239], v[44:45]
	v_pk_mul_f32 v[46:47], v[240:241], v[46:47]
	v_pk_mul_f32 v[42:43], v[108:109], v[42:43]
	v_pk_mul_f32 v[38:39], v[104:105], v[38:39]
	v_pk_mul_f32 v[32:33], v[98:99], v[32:33]
	ds_read_b128 v[98:101], v96 offset:36224
	ds_read_b128 v[102:105], v96 offset:36256
	ds_read_b128 v[106:109], v96 offset:36288
	ds_read_b128 v[238:241], v96 offset:36320
	s_add_i32 s61, s44, 0
	s_waitcnt lgkmcnt(3)
	v_pk_mul_f32 v[18:19], v[100:101], v[18:19]
	s_waitcnt lgkmcnt(2)
	v_pk_mul_f32 v[20:21], v[102:103], v[20:21]
	v_pk_mul_f32 v[22:23], v[104:105], v[22:23]
	v_pk_mul_f32 v[16:17], v[98:99], v[16:17]
	s_waitcnt lgkmcnt(0)
	v_mul_f32_e64 v28, v238, v28
	v_mul_f32_e64 v29, v239, v29
	v_mul_f32_e64 v24, v106, v24
	v_mul_f32_e64 v25, v107, v25
	v_pk_mul_f32 v[30:31], v[240:241], v[30:31]
	v_pk_mul_f32 v[26:27], v[108:109], v[26:27]
	s_add_i32 s61, s61, 0x11c00
	s_lshl_b32 s44, s24, 2
	s_add_i32 s44, s61, s44
	ds_read_b128 v[98:101], v97
	ds_read_b128 v[102:105], v97 offset:4608
	ds_read_b128 v[210:213], v97 offset:9216
	ds_read_b128 v[214:217], v97 offset:13824
	ds_read_b128 v[246:249], v97 offset:32
	ds_read_b128 v[250:253], v97 offset:4640
	s_waitcnt vmcnt(15) lgkmcnt(5)
	v_mfma_f32_32x32x16_bf16 v[64:79], v[98:101], v[92:95], v[64:79]
	ds_read_b128 v[98:101], v97 offset:9248
	s_waitcnt lgkmcnt(5)
	v_mfma_f32_32x32x16_bf16 v[48:63], v[102:105], v[92:95], v[48:63]
	ds_read_b128 v[102:105], v97 offset:13856
	s_waitcnt lgkmcnt(5)
	v_mfma_f32_32x32x16_bf16 v[32:47], v[210:213], v[92:95], v[32:47]
	ds_read_b128 v[210:213], v97 offset:64
	s_waitcnt lgkmcnt(5)
	v_mfma_f32_32x32x16_bf16 v[16:31], v[214:217], v[92:95], v[16:31]
	ds_read_b128 v[214:217], v97 offset:4672
	s_waitcnt vmcnt(14) lgkmcnt(5)
	v_mfma_f32_32x32x16_bf16 v[64:79], v[246:249], v[88:91], v[64:79]
	ds_read_b128 v[246:249], v97 offset:9280
	s_waitcnt lgkmcnt(5)
	v_mfma_f32_32x32x16_bf16 v[48:63], v[250:253], v[88:91], v[48:63]
	ds_read_b128 v[250:253], v97 offset:13888
	s_waitcnt lgkmcnt(5)
	v_mfma_f32_32x32x16_bf16 v[32:47], v[98:101], v[88:91], v[32:47]
	ds_read_b128 v[98:101], v97 offset:96
	s_waitcnt lgkmcnt(5)
	v_mfma_f32_32x32x16_bf16 v[16:31], v[102:105], v[88:91], v[16:31]
	ds_read_b128 v[102:105], v97 offset:4704
	s_waitcnt vmcnt(13) lgkmcnt(5)
	v_mfma_f32_32x32x16_bf16 v[64:79], v[210:213], v[84:87], v[64:79]
	ds_read_b128 v[210:213], v97 offset:9312
	s_waitcnt lgkmcnt(5)
	v_mfma_f32_32x32x16_bf16 v[48:63], v[214:217], v[84:87], v[48:63]
	ds_read_b128 v[214:217], v97 offset:13920
	s_waitcnt lgkmcnt(5)
	v_mfma_f32_32x32x16_bf16 v[32:47], v[246:249], v[84:87], v[32:47]
	s_waitcnt lgkmcnt(4)
	v_mfma_f32_32x32x16_bf16 v[16:31], v[250:253], v[84:87], v[16:31]
	s_waitcnt vmcnt(12) lgkmcnt(3)
	v_mfma_f32_32x32x16_bf16 v[64:79], v[98:101], v[80:83], v[64:79]
	s_waitcnt lgkmcnt(2)
	v_mfma_f32_32x32x16_bf16 v[48:63], v[102:105], v[80:83], v[48:63]
	s_waitcnt lgkmcnt(1)
	v_mfma_f32_32x32x16_bf16 v[32:47], v[210:213], v[80:83], v[32:47]
	s_waitcnt lgkmcnt(0)
	v_mfma_f32_32x32x16_bf16 v[16:31], v[214:217], v[80:83], v[16:31]
	ds_read_b128 v[246:249], v183 offset:18432
	ds_read_b128 v[250:253], v183 offset:27136
	ds_read_b128 v[210:213], v183 offset:18464
	ds_read_b128 v[214:217], v183 offset:27168
	s_nop 4
	v_cvt_pk_bf16_f32 v238, v64, v65
	v_cvt_pk_bf16_f32 v239, v66, v67
	v_cvt_pk_bf16_f32 v240, v68, v69
	v_cvt_pk_bf16_f32 v241, v70, v71
	v_cvt_pk_bf16_f32 v242, v72, v73
	v_cvt_pk_bf16_f32 v243, v74, v75
	v_cvt_pk_bf16_f32 v244, v76, v77
	v_cvt_pk_bf16_f32 v245, v78, v79
	s_waitcnt lgkmcnt(3)
	v_mfma_f32_32x32x16_bf16 v[96:111], v[238:241], v[246:249], 0
	s_waitcnt lgkmcnt(2)
	v_mfma_f32_32x32x16_bf16 v[80:95], v[238:241], v[250:253], 0
	v_cvt_pk_bf16_f32 v238, v48, v49
	v_cvt_pk_bf16_f32 v239, v50, v51
	v_cvt_pk_bf16_f32 v240, v52, v53
	v_cvt_pk_bf16_f32 v241, v54, v55
	ds_read_b128 v[246:249], v183 offset:18496
	ds_read_b128 v[250:253], v183 offset:27200
	s_waitcnt lgkmcnt(3)
	v_mfma_f32_32x32x16_bf16 v[96:111], v[242:245], v[210:213], v[96:111]
	s_waitcnt lgkmcnt(2)
	v_mfma_f32_32x32x16_bf16 v[80:95], v[242:245], v[214:217], v[80:95]
	v_cvt_pk_bf16_f32 v242, v56, v57
	v_cvt_pk_bf16_f32 v243, v58, v59
	v_cvt_pk_bf16_f32 v244, v60, v61
	v_cvt_pk_bf16_f32 v245, v62, v63
	ds_read_b128 v[210:213], v183 offset:18528
	ds_read_b128 v[214:217], v183 offset:27232
	s_waitcnt lgkmcnt(3)
	v_mfma_f32_32x32x16_bf16 v[96:111], v[238:241], v[246:249], v[96:111]
	s_waitcnt lgkmcnt(2)
	v_mfma_f32_32x32x16_bf16 v[80:95], v[238:241], v[250:253], v[80:95]
	v_cvt_pk_bf16_f32 v238, v32, v33
	v_cvt_pk_bf16_f32 v239, v34, v35
	v_cvt_pk_bf16_f32 v240, v36, v37
	v_cvt_pk_bf16_f32 v241, v38, v39
	ds_read_b128 v[246:249], v183 offset:18560
	ds_read_b128 v[250:253], v183 offset:27264
	s_waitcnt lgkmcnt(3)
	v_mfma_f32_32x32x16_bf16 v[96:111], v[242:245], v[210:213], v[96:111]
	s_waitcnt lgkmcnt(2)
	v_mfma_f32_32x32x16_bf16 v[80:95], v[242:245], v[214:217], v[80:95]
	v_cvt_pk_bf16_f32 v242, v40, v41
	v_cvt_pk_bf16_f32 v243, v42, v43
	v_cvt_pk_bf16_f32 v244, v44, v45
	v_cvt_pk_bf16_f32 v245, v46, v47
	ds_read_b128 v[210:213], v183 offset:18592
	ds_read_b128 v[214:217], v183 offset:27296
	s_waitcnt lgkmcnt(3)
	v_mfma_f32_32x32x16_bf16 v[96:111], v[238:241], v[246:249], v[96:111]
	s_waitcnt lgkmcnt(2)
	v_mfma_f32_32x32x16_bf16 v[80:95], v[238:241], v[250:253], v[80:95]
	v_cvt_pk_bf16_f32 v238, v16, v17
	v_cvt_pk_bf16_f32 v239, v18, v19
	v_cvt_pk_bf16_f32 v240, v20, v21
	v_cvt_pk_bf16_f32 v241, v22, v23
	ds_read_b128 v[246:249], v183 offset:18624
	ds_read_b128 v[250:253], v183 offset:27328
	s_waitcnt lgkmcnt(3)
	v_mfma_f32_32x32x16_bf16 v[96:111], v[242:245], v[210:213], v[96:111]
	s_waitcnt lgkmcnt(2)
	v_mfma_f32_32x32x16_bf16 v[80:95], v[242:245], v[214:217], v[80:95]
	v_cvt_pk_bf16_f32 v242, v24, v25
	v_cvt_pk_bf16_f32 v243, v26, v27
	v_cvt_pk_bf16_f32 v244, v28, v29
	v_cvt_pk_bf16_f32 v245, v30, v31
	ds_read_b128 v[210:213], v183 offset:18656
	ds_read_b128 v[214:217], v183 offset:27360
	s_waitcnt lgkmcnt(3)
	v_mfma_f32_32x32x16_bf16 v[96:111], v[238:241], v[246:249], v[96:111]
	s_waitcnt lgkmcnt(2)
	v_mfma_f32_32x32x16_bf16 v[80:95], v[238:241], v[250:253], v[80:95]
	s_waitcnt lgkmcnt(1)
	v_mfma_f32_32x32x16_bf16 v[96:111], v[242:245], v[210:213], v[96:111]
	s_waitcnt lgkmcnt(0)
	v_mfma_f32_32x32x16_bf16 v[80:95], v[242:245], v[214:217], v[80:95]
	v_lshl_add_u32 v183, v176, 2, s44
	s_nop 0
	s_nop 7
	v_mul_f32_e32 v185, v97, v97
	v_fmac_f32_e32 v185, v96, v96
	v_fmac_f32_e32 v185, v98, v98
	v_fmac_f32_e32 v185, v99, v99
	v_fmac_f32_e32 v185, v100, v100
	v_fmac_f32_e32 v185, v101, v101
	v_fmac_f32_e32 v185, v102, v102
	v_fmac_f32_e32 v185, v103, v103
	v_fmac_f32_e32 v185, v104, v104
	v_fmac_f32_e32 v185, v105, v105
	v_fmac_f32_e32 v185, v106, v106
	v_fmac_f32_e32 v185, v107, v107
	v_fmac_f32_e32 v185, v108, v108
	v_fmac_f32_e32 v185, v109, v109
	v_fmac_f32_e32 v185, v110, v110
	v_fmac_f32_e32 v185, v111, v111
	v_mov_b32_e32 v187, v185
	s_nop 1
	v_permlane32_swap_b32_e32 v185, v187
	s_and_saveexec_b64 s[44:45], s[42:43]
	v_add_f32_e32 v185, v185, v187
	ds_write_b32 v183, v185
	s_or_b64 exec, exec, s[44:45]
	v_mul_f32_e32 v185, v81, v81
	v_fmac_f32_e32 v185, v80, v80
	v_fmac_f32_e32 v185, v82, v82
	v_fmac_f32_e32 v185, v83, v83
	v_fmac_f32_e32 v185, v84, v84
	v_fmac_f32_e32 v185, v85, v85
	v_fmac_f32_e32 v185, v86, v86
	v_fmac_f32_e32 v185, v87, v87
	v_fmac_f32_e32 v185, v88, v88
	v_fmac_f32_e32 v185, v89, v89
	v_fmac_f32_e32 v185, v90, v90
	v_fmac_f32_e32 v185, v91, v91
	v_fmac_f32_e32 v185, v92, v92
	v_fmac_f32_e32 v185, v93, v93
	v_fmac_f32_e32 v185, v94, v94
	v_fmac_f32_e32 v185, v95, v95
	v_mov_b32_e32 v187, v185
	s_nop 1
	v_permlane32_swap_b32_e32 v185, v187
	s_and_saveexec_b64 s[44:45], s[42:43]
	v_add_f32_e32 v185, v185, v187
	ds_write_b32 v183, v185 offset:128
	s_or_b64 exec, exec, s[44:45]
	s_waitcnt lgkmcnt(0)
	s_barrier
	v_lshl_add_u32 v183, v176, 2, s61
	ds_read_b32 v210, v183
	ds_read_b32 v211, v183 offset:256
	ds_read_b32 v212, v183 offset:512
	ds_read_b32 v213, v183 offset:768
	ds_read_b32 v214, v183 offset:1024
	ds_read_b32 v215, v183 offset:1280
	ds_read_b32 v216, v183 offset:1536
	ds_read_b32 v217, v183 offset:1792
	ds_read_b32 v246, v183 offset:128
	ds_read_b32 v247, v183 offset:384
	ds_read_b32 v248, v183 offset:640
	ds_read_b32 v249, v183 offset:896
	ds_read_b32 v250, v183 offset:1152
	ds_read_b32 v251, v183 offset:1408
	ds_read_b32 v252, v183 offset:1664
	ds_read_b32 v253, v183 offset:1920
	s_add_i32 s44, s55, -1
	s_cmp_ge_u32 s44, s60
	s_waitcnt lgkmcnt(8)
	v_add_f32_e32 v210, v210, v211
	v_add_f32_e32 v212, v212, v213
	v_add_f32_e32 v214, v214, v215
	v_add_f32_e32 v216, v216, v217
	v_add_f32_e32 v210, v210, v212
	v_add_f32_e32 v214, v214, v216
	v_add_f32_e32 v185, v210, v214
	v_fmamk_f32 v185, v185, 0x3b800000, v207
	v_rsq_f32_e32 v210, v185
	v_add_u32_e32 v185, s24, v232
	v_pk_mul_f32 v[96:97], v[210:211], v[96:97] op_sel_hi:[0,1]
	v_pk_mul_f32 v[98:99], v[210:211], v[98:99] op_sel_hi:[0,1]
	v_pk_mul_f32 v[96:97], v[2:3], v[96:97]
	v_pk_mul_f32 v[98:99], v[4:5], v[98:99]
	v_cvt_pk_bf16_f32 v96, v96, v97
	v_cvt_pk_bf16_f32 v97, v98, v99
	v_pk_mul_f32 v[98:99], v[210:211], v[100:101] op_sel_hi:[0,1]
	v_pk_mul_f32 v[100:101], v[210:211], v[102:103] op_sel_hi:[0,1]
	v_pk_mul_f32 v[98:99], v[6:7], v[98:99]
	v_pk_mul_f32 v[100:101], v[8:9], v[100:101]
	v_cvt_pk_bf16_f32 v98, v98, v99
	v_cvt_pk_bf16_f32 v99, v100, v101
	ds_write2_b64 v185, v[96:97], v[98:99] offset1:2
	v_pk_mul_f32 v[96:97], v[210:211], v[104:105] op_sel_hi:[0,1]
	v_pk_mul_f32 v[98:99], v[210:211], v[106:107] op_sel_hi:[0,1]
	v_pk_mul_f32 v[96:97], v[10:11], v[96:97]
	v_pk_mul_f32 v[98:99], v[12:13], v[98:99]
	v_cvt_pk_bf16_f32 v96, v96, v97
	v_cvt_pk_bf16_f32 v97, v98, v99
	v_pk_mul_f32 v[98:99], v[210:211], v[108:109] op_sel_hi:[0,1]
	v_pk_mul_f32 v[100:101], v[210:211], v[110:111] op_sel_hi:[0,1]
	v_pk_mul_f32 v[98:99], v[112:113], v[98:99]
	v_pk_mul_f32 v[100:101], v[114:115], v[100:101]
	v_cvt_pk_bf16_f32 v98, v98, v99
	v_cvt_pk_bf16_f32 v99, v100, v101
	ds_write2_b64 v185, v[96:97], v[98:99] offset0:4 offset1:6
	s_waitcnt lgkmcnt(0)
	v_add_f32_e32 v246, v246, v247
	v_add_f32_e32 v248, v248, v249
	v_add_f32_e32 v250, v250, v251
	v_add_f32_e32 v252, v252, v253
	v_add_f32_e32 v246, v246, v248
	v_add_f32_e32 v250, v250, v252
	v_add_f32_e32 v96, v246, v250
	v_fmamk_f32 v96, v96, 0x3b800000, v207
	v_rsq_f32_e32 v96, v96
	s_nop 0
	v_pk_mul_f32 v[80:81], v[96:97], v[80:81] op_sel_hi:[0,1]
	v_pk_mul_f32 v[82:83], v[96:97], v[82:83] op_sel_hi:[0,1]
	v_pk_mul_f32 v[80:81], v[2:3], v[80:81]
	v_pk_mul_f32 v[82:83], v[4:5], v[82:83]
	v_cvt_pk_bf16_f32 v80, v80, v81
	v_cvt_pk_bf16_f32 v81, v82, v83
	v_pk_mul_f32 v[82:83], v[96:97], v[84:85] op_sel_hi:[0,1]
	v_pk_mul_f32 v[84:85], v[96:97], v[86:87] op_sel_hi:[0,1]
	v_pk_mul_f32 v[82:83], v[6:7], v[82:83]
	v_pk_mul_f32 v[84:85], v[8:9], v[84:85]
	v_cvt_pk_bf16_f32 v82, v82, v83
	v_cvt_pk_bf16_f32 v83, v84, v85
	ds_write2_b64 v177, v[80:81], v[82:83] offset1:2
	v_pk_mul_f32 v[80:81], v[96:97], v[88:89] op_sel_hi:[0,1]
	v_pk_mul_f32 v[82:83], v[96:97], v[90:91] op_sel_hi:[0,1]
	v_pk_mul_f32 v[80:81], v[10:11], v[80:81]
	v_pk_mul_f32 v[82:83], v[12:13], v[82:83]
	v_cvt_pk_bf16_f32 v80, v80, v81
	v_cvt_pk_bf16_f32 v81, v82, v83
	v_pk_mul_f32 v[82:83], v[96:97], v[92:93] op_sel_hi:[0,1]
	v_pk_mul_f32 v[84:85], v[96:97], v[94:95] op_sel_hi:[0,1]
	v_pk_mul_f32 v[82:83], v[112:113], v[82:83]
	v_pk_mul_f32 v[84:85], v[114:115], v[84:85]
	v_cvt_pk_bf16_f32 v82, v82, v83
	v_cvt_pk_bf16_f32 v83, v84, v85
	ds_write2_b64 v177, v[80:81], v[82:83] offset0:4 offset1:6
	s_cbranch_scc1 .LBB0_123
	s_bitcmp1_b32 s44, 0
	s_cselect_b32 s44, 0x8e00, 0
	s_add_i32 s61, s44, 0
	v_add_u32_e32 v80, s61, v14
	v_add_u32_e32 v81, v80, v15
	v_add_u32_e32 v80, v80, v165
	s_waitcnt vmcnt(11)
	ds_write_b128 v81, v[116:119]
	s_waitcnt vmcnt(10)
	ds_write_b128 v80, v[120:123]
	v_add_u32_e32 v80, s61, v172
	v_add_u32_e32 v81, v80, v173
	v_add_u32_e32 v80, v80, v228
	s_waitcnt vmcnt(9)
	ds_write_b128 v81, v[124:127] offset:18432
	s_waitcnt vmcnt(8)
	ds_write_b128 v80, v[128:131] offset:18432
	s_and_saveexec_b64 s[44:45], vcc
	v_add_u32_e32 v80, s61, v229
	ds_write_b32 v80, v1 offset:35840
	s_or_b64 exec, exec, s[44:45]

.LBB0_196:
	global_load_dwordx4 v[30:33], v[40:41], off nt
	global_load_dwordx4 v[26:29], v[40:41], off offset:1024 nt
	global_load_dwordx4 v[22:25], v[40:41], off offset:2048 nt
	global_load_dwordx4 v[18:21], v[40:41], off offset:3072 nt
	s_add_i32 s9, s21, s7
	s_cmp_lt_i32 s9, 0x8000
	s_cselect_b32 s24, s9, s7
	s_ashr_i32 s25, s24, 31
	s_lshl_b64 s[38:39], s[24:25], 12
	v_lshl_add_u64 v[58:59], v[34:35], 0, s[38:39]
	global_load_dwordx4 v[46:49], v[58:59], off nt
	global_load_dwordx4 v[50:53], v[58:59], off offset:1024 nt
	global_load_dwordx4 v[54:57], v[58:59], off offset:2048 nt
	s_nop 0
	global_load_dwordx4 v[58:61], v[58:59], off offset:3072 nt
	s_lshr_b32 s9, s7, 11
	s_mul_i32 s26, s9, 0x1800
	s_ashr_i32 s27, s26, 31
	s_lshl_b64 s[26:27], s[26:27], 2
	s_add_u32 s26, s36, s26
	s_addc_u32 s27, s37, s27
	s_add_u32 s38, s26, 0x1000
	s_addc_u32 s39, s27, 0
	s_lshr_b32 s9, s24, 11
	global_load_dwordx4 v[62:65], v1, s[26:27]
	global_load_dwordx4 v[66:69], v1, s[26:27] offset:1024
	global_load_dwordx4 v[70:73], v1, s[26:27] offset:2048
	global_load_dwordx4 v[74:77], v1, s[26:27] offset:3072
	s_mul_i32 s26, s9, 0x1800
	s_ashr_i32 s27, s26, 31
	s_lshl_b64 s[26:27], s[26:27], 2
	global_load_dwordx4 v[78:81], v1, s[38:39]
	global_load_dwordx4 v[82:85], v42, s[38:39]
	global_load_dwordx4 v[86:89], v43, s[38:39]
	global_load_dwordx4 v[90:93], v44, s[38:39]
	s_add_u32 s26, s36, s26
	s_addc_u32 s27, s37, s27
	s_add_u32 s38, s26, 0x1000
	s_addc_u32 s39, s27, 0
	global_load_dwordx4 v[94:97], v1, s[26:27]
	global_load_dwordx4 v[98:101], v1, s[26:27] offset:1024
	global_load_dwordx4 v[102:105], v1, s[26:27] offset:2048
	global_load_dwordx4 v[106:109], v1, s[26:27] offset:3072
	global_load_dwordx4 v[110:113], v1, s[38:39]
	global_load_dwordx4 v[114:117], v42, s[38:39]
	global_load_dwordx4 v[118:121], v43, s[38:39]
	global_load_dwordx4 v[122:125], v44, s[38:39]
	s_lshl_b64 s[24:25], s[24:25], 11
	s_add_i32 s7, s7, s8
	v_lshl_add_u64 v[40:41], v[40:41], 0, s[28:29]
	v_lshl_add_u64 v[126:127], v[36:37], 0, s[24:25]
	s_cmpk_gt_i32 s7, 0x7fff
	s_waitcnt vmcnt(23)
	v_mul_f32_e32 v45, v31, v31
	v_mul_f32_e32 v128, v33, v33
	s_waitcnt vmcnt(22)
	v_mul_f32_e32 v129, v27, v27
	v_mul_f32_e32 v130, v29, v29
	s_waitcnt vmcnt(21)
	v_mul_f32_e32 v131, v23, v23
	v_mul_f32_e32 v132, v25, v25
	v_fmac_f32_e32 v45, v30, v30
	v_fmac_f32_e32 v128, v32, v32
	v_fmac_f32_e32 v129, v26, v26
	v_fmac_f32_e32 v130, v28, v28
	s_waitcnt vmcnt(20)
	v_mul_f32_e32 v133, v19, v19
	v_mul_f32_e32 v134, v21, v21
	v_fmac_f32_e32 v131, v22, v22
	v_fmac_f32_e32 v132, v24, v24
	v_add_f32_e32 v45, v45, v128
	v_add_f32_e32 v128, v129, v130
	v_fmac_f32_e32 v133, v18, v18
	v_fmac_f32_e32 v134, v20, v20
	v_add_f32_e32 v129, v131, v132
	v_add_f32_e32 v45, v45, v128
	v_add_f32_e32 v130, v133, v134
	v_add_f32_e32 v45, v45, v129
	v_add_f32_e32 v45, v45, v130
	s_waitcnt vmcnt(19)
	v_mul_f32_e32 v128, v47, v47
	v_mul_f32_e32 v129, v49, v49
	s_waitcnt vmcnt(18)
	v_mul_f32_e32 v130, v51, v51
	v_mul_f32_e32 v131, v53, v53
	v_add_f32_dpp v45, v45, v45 quad_perm:[1,0,3,2] row_mask:0xf bank_mask:0xf bound_ctrl:1
	s_waitcnt vmcnt(17)
	v_mul_f32_e32 v132, v55, v55
	v_mul_f32_e32 v133, v57, v57
	v_fmac_f32_e32 v128, v46, v46
	v_fmac_f32_e32 v129, v48, v48
	v_fmac_f32_e32 v130, v50, v50
	v_fmac_f32_e32 v131, v52, v52
	v_add_f32_dpp v45, v45, v45 quad_perm:[2,3,0,1] row_mask:0xf bank_mask:0xf bound_ctrl:1
	s_waitcnt vmcnt(16)
	v_mul_f32_e32 v134, v59, v59
	v_mul_f32_e32 v135, v61, v61
	v_fmac_f32_e32 v132, v54, v54
	v_fmac_f32_e32 v133, v56, v56
	v_add_f32_e32 v128, v128, v129
	v_add_f32_e32 v129, v130, v131
	v_add_f32_dpp v45, v45, v45 row_half_mirror row_mask:0xf bank_mask:0xf bound_ctrl:1
	v_fmac_f32_e32 v134, v58, v58
	v_fmac_f32_e32 v135, v60, v60
	v_add_f32_e32 v130, v132, v133
	v_add_f32_e32 v128, v128, v129
	v_add_f32_dpp v45, v45, v45 row_mirror row_mask:0xf bank_mask:0xf bound_ctrl:1
	v_add_f32_e32 v131, v134, v135
	v_add_f32_e32 v128, v128, v130
	v_mov_b32_e32 v129, v45
	v_add_f32_e32 v128, v128, v131
	s_nop 0
	v_permlane16_swap_b32_e32 v45, v129
	v_add_f32_e32 v45, v45, v129
	v_add_f32_dpp v128, v128, v128 quad_perm:[1,0,3,2] row_mask:0xf bank_mask:0xf bound_ctrl:1
	v_mov_b32_e32 v129, v45
	s_nop 1
	v_permlane32_swap_b32_e32 v45, v129
	v_add_f32_dpp v128, v128, v128 quad_perm:[2,3,0,1] row_mask:0xf bank_mask:0xf bound_ctrl:1
	v_add_f32_e32 v45, v45, v129
	v_fmamk_f32 v45, v45, 0x3a800000, v207
	v_add_f32_dpp v128, v128, v128 row_half_mirror row_mask:0xf bank_mask:0xf bound_ctrl:1
	s_waitcnt vmcnt(11)
	v_pk_add_f32 v[78:79], v[78:79], 1.0 op_sel_hi:[1,0]
	v_pk_add_f32 v[80:81], v[80:81], 1.0 op_sel_hi:[1,0]
	v_add_f32_dpp v129, v128, v128 row_mirror row_mask:0xf bank_mask:0xf bound_ctrl:1
	v_mov_b32_e32 v130, v129
	s_nop 1
	v_permlane16_swap_b32_e32 v129, v130
	v_rsq_f32_e32 v128, v45
	v_add_f32_e32 v45, v129, v130
	v_mov_b32_e32 v129, v45
	s_nop 1
	v_permlane32_swap_b32_e32 v45, v129
	v_add_f32_e32 v45, v45, v129
	v_pk_mul_f32 v[30:31], v[30:31], v[128:129] op_sel_hi:[1,0]
	v_fmamk_f32 v45, v45, 0x3a800000, v207
	v_pk_mul_f32 v[30:31], v[2:3], v[30:31]
	v_pk_mul_f32 v[32:33], v[32:33], v[128:129] op_sel_hi:[1,0]
	v_pk_mul_f32 v[20:21], v[20:21], v[128:129] op_sel_hi:[1,0]
	v_pk_mul_f32 v[18:19], v[18:19], v[128:129] op_sel_hi:[1,0]
	v_pk_fma_f32 v[30:31], v[78:79], v[30:31], v[62:63]
	v_rsq_f32_e32 v62, v45
	s_waitcnt vmcnt(8)
	v_pk_add_f32 v[92:93], v[92:93], 1.0 op_sel_hi:[1,0]
	v_pk_add_f32 v[90:91], v[90:91], 1.0 op_sel_hi:[1,0]
	v_pk_mul_f32 v[28:29], v[28:29], v[128:129] op_sel_hi:[1,0]
	v_pk_mul_f32 v[26:27], v[26:27], v[128:129] op_sel_hi:[1,0]
	v_pk_mul_f32 v[24:25], v[24:25], v[128:129] op_sel_hi:[1,0]
	v_pk_mul_f32 v[22:23], v[22:23], v[128:129] op_sel_hi:[1,0]
	v_pk_mul_f32 v[32:33], v[4:5], v[32:33]
	v_pk_mul_f32 v[18:19], v[14:15], v[18:19]
	v_pk_mul_f32 v[20:21], v[16:17], v[20:21]
	v_pk_add_f32 v[84:85], v[84:85], 1.0 op_sel_hi:[1,0]
	v_pk_add_f32 v[82:83], v[82:83], 1.0 op_sel_hi:[1,0]
	v_pk_add_f32 v[88:89], v[88:89], 1.0 op_sel_hi:[1,0]
	v_pk_add_f32 v[86:87], v[86:87], 1.0 op_sel_hi:[1,0]
	v_pk_mul_f32 v[26:27], v[6:7], v[26:27]
	v_pk_mul_f32 v[28:29], v[8:9], v[28:29]
	v_pk_mul_f32 v[22:23], v[10:11], v[22:23]
	v_pk_mul_f32 v[24:25], v[12:13], v[24:25]
	v_pk_fma_f32 v[32:33], v[80:81], v[32:33], v[64:65]
	v_pk_fma_f32 v[20:21], v[20:21], v[92:93], v[76:77]
	v_pk_fma_f32 v[18:19], v[18:19], v[90:91], v[74:75]
	v_pk_fma_f32 v[28:29], v[28:29], v[84:85], v[68:69]
	v_pk_fma_f32 v[26:27], v[26:27], v[82:83], v[66:67]
	v_pk_fma_f32 v[24:25], v[24:25], v[88:89], v[72:73]
	v_pk_fma_f32 v[22:23], v[22:23], v[86:87], v[70:71]
	v_cvt_pk_bf16_f32 v30, v30, v31
	v_cvt_pk_bf16_f32 v31, v32, v33
	v_cvt_pk_bf16_f32 v18, v18, v19
	v_cvt_pk_bf16_f32 v19, v20, v21
	v_cvt_pk_bf16_f32 v26, v26, v27
	v_cvt_pk_bf16_f32 v27, v28, v29
	v_cvt_pk_bf16_f32 v22, v22, v23
	v_cvt_pk_bf16_f32 v23, v24, v25
	global_store_dwordx2 v[38:39], v[30:31], off sc1
	global_store_dwordx2 v[38:39], v[26:27], off offset:512 sc1
	global_store_dwordx2 v[38:39], v[22:23], off offset:1024 sc1
	global_store_dwordx2 v[38:39], v[18:19], off offset:1536 sc1
	v_pk_mul_f32 v[18:19], v[48:49], v[62:63] op_sel_hi:[1,0]
	v_pk_mul_f32 v[20:21], v[46:47], v[62:63] op_sel_hi:[1,0]
	s_waitcnt vmcnt(7)
	v_pk_add_f32 v[112:113], v[112:113], 1.0 op_sel_hi:[1,0]
	v_pk_add_f32 v[110:111], v[110:111], 1.0 op_sel_hi:[1,0]
	v_pk_mul_f32 v[22:23], v[52:53], v[62:63] op_sel_hi:[1,0]
	v_pk_mul_f32 v[24:25], v[50:51], v[62:63] op_sel_hi:[1,0]
	v_pk_mul_f32 v[26:27], v[56:57], v[62:63] op_sel_hi:[1,0]
	v_pk_mul_f32 v[28:29], v[54:55], v[62:63] op_sel_hi:[1,0]
	v_pk_mul_f32 v[30:31], v[60:61], v[62:63] op_sel_hi:[1,0]
	v_pk_mul_f32 v[32:33], v[58:59], v[62:63] op_sel_hi:[1,0]
	v_pk_mul_f32 v[20:21], v[2:3], v[20:21]
	v_pk_mul_f32 v[18:19], v[4:5], v[18:19]
	s_waitcnt vmcnt(6)
	v_pk_add_f32 v[116:117], v[116:117], 1.0 op_sel_hi:[1,0]
	v_pk_add_f32 v[114:115], v[114:115], 1.0 op_sel_hi:[1,0]
	s_waitcnt vmcnt(5)
	v_pk_add_f32 v[120:121], v[120:121], 1.0 op_sel_hi:[1,0]
	v_pk_add_f32 v[118:119], v[118:119], 1.0 op_sel_hi:[1,0]
	s_waitcnt vmcnt(4)
	v_pk_add_f32 v[124:125], v[124:125], 1.0 op_sel_hi:[1,0]
	v_pk_add_f32 v[122:123], v[122:123], 1.0 op_sel_hi:[1,0]
	v_pk_mul_f32 v[24:25], v[6:7], v[24:25]
	v_pk_mul_f32 v[22:23], v[8:9], v[22:23]
	v_pk_mul_f32 v[28:29], v[10:11], v[28:29]
	v_pk_mul_f32 v[26:27], v[12:13], v[26:27]
	v_pk_mul_f32 v[32:33], v[14:15], v[32:33]
	v_pk_mul_f32 v[30:31], v[16:17], v[30:31]
	v_pk_fma_f32 v[18:19], v[18:19], v[112:113], v[96:97]
	v_pk_fma_f32 v[20:21], v[20:21], v[110:111], v[94:95]
	v_lshl_add_u64 v[38:39], v[38:39], 0, s[22:23]
	v_pk_fma_f32 v[22:23], v[22:23], v[116:117], v[100:101]
	v_pk_fma_f32 v[24:25], v[24:25], v[114:115], v[98:99]
	v_pk_fma_f32 v[26:27], v[26:27], v[120:121], v[104:105]
	v_pk_fma_f32 v[28:29], v[28:29], v[118:119], v[102:103]
	v_pk_fma_f32 v[30:31], v[30:31], v[124:125], v[108:109]
	v_pk_fma_f32 v[32:33], v[32:33], v[122:123], v[106:107]
	v_cvt_pk_bf16_f32 v20, v20, v21
	v_cvt_pk_bf16_f32 v21, v18, v19
	v_cvt_pk_bf16_f32 v18, v24, v25
	v_cvt_pk_bf16_f32 v19, v22, v23
	v_cvt_pk_bf16_f32 v22, v28, v29
	v_cvt_pk_bf16_f32 v23, v26, v27
	v_cvt_pk_bf16_f32 v24, v32, v33
	v_cvt_pk_bf16_f32 v25, v30, v31
	global_store_dwordx2 v[126:127], v[20:21], off sc1
	global_store_dwordx2 v[126:127], v[18:19], off offset:512 sc1
	global_store_dwordx2 v[126:127], v[22:23], off offset:1024 sc1
	global_store_dwordx2 v[126:127], v[24:25], off offset:1536 sc1
	s_cbranch_scc0 .LBB0_196

.LBB0_435:
	s_cmp_eq_u32 s31, 2
	s_cbranch_scc1 .Lepi_ya
	s_cmp_eq_u32 s31, 6
	s_cbranch_scc1 .Lepi_yb
	s_cmp_eq_u32 s31, 7
	s_cbranch_scc1 .Lepi_wout
	s_cmp_eq_u32 s31, 9
	s_cbranch_scc1 .Lepi_w2
	s_cmp_eq_u32 s31, 3
	s_cbranch_scc1 .Lepi_qup
	s_cmp_eq_u32 s31, 4
	s_cbranch_scc1 .Lepi_kup
	s_cmp_eq_u32 s31, 5
	s_cbranch_scc1 .Lepi_vupt
	s_lshl_b32 s9, s9, 8
	s_add_i32 s9, s9, s60
	s_lshl_b32 s78, s8, 8
	v_or_b32_e32 v154, s9, v1
	s_ashr_i32 s41, s9, 11
	v_ashrrev_i32_e32 v155, 31, v154
	s_or_b32 s38, s78, s26
	s_mul_hi_i32 s48, s41, 0x6000
	s_mulk_i32 s41, 0x6000
	v_lshlrev_b64 v[158:159], 10, v[154:155]
	v_lshlrev_b64 v[170:171], 13, v[154:155]
	v_lshlrev_b64 v[156:157], 7, v[154:155]
	v_cmp_gt_i32_e64 s[46:47], s33, v154
	v_or_b32_e32 v152, s38, v176
	s_cmp_lt_i32 s31, 5
	s_mov_b64 s[74:75], -1
	s_cbranch_scc1 .LBB0_454
	s_cmp_lt_i32 s31, 7
	s_cbranch_scc1 .LBB0_448
	s_cmp_lt_i32 s31, 8
	s_cbranch_scc1 .LBB0_445
	s_cmp_lt_i32 s31, 9
	s_cbranch_scc1 .LBB0_442
	s_cmp_eq_u32 s31, 9
	s_cbranch_scc0 .LBB0_441
	s_add_u32 s68, s36, s41
	v_ashrrev_i32_e32 v153, 31, v152
	s_addc_u32 s69, s37, s48
	v_lshlrev_b64 v[168:169], 2, v[152:153]
	v_lshl_add_u64 v[164:165], s[68:69], 0, v[168:169]
	v_lshlrev_b64 v[172:173], 2, v[158:159]
	v_add_co_u32_e32 v130, vcc, 0x5000, v164
	v_lshl_add_u64 v[134:135], s[94:95], 0, v[172:173]
	s_nop 0
	v_addc_co_u32_e32 v131, vcc, 0, v165, vcc
	v_lshl_add_u64 v[174:175], v[134:135], 0, v[168:169]
	s_mov_b64 s[68:69], 0x5000
	global_load_dwordx4 v[130:133], v[130:131], off
	s_nop 0
	global_load_dwordx4 v[134:137], v[174:175], off offset:16
	global_load_dwordx4 v[160:163], v[174:175], off
	v_lshl_add_u64 v[164:165], v[164:165], 0, s[68:69]
	global_load_dwordx4 v[164:167], v[164:165], off offset:16
	v_lshl_add_u64 v[172:173], s[54:55], 0, v[172:173]
	v_lshl_add_u64 v[168:169], v[172:173], 0, v[168:169]
	v_cndmask_b32_e64 v169, v169, v175, s[42:43]
	v_cndmask_b32_e64 v168, v168, v174, s[42:43]
	s_waitcnt vmcnt(0)
	v_pk_fma_f32 v[132:133], v[128:129], v[132:133], v[162:163]
	v_pk_fma_f32 v[130:131], v[126:127], v[130:131], v[160:161]
	v_pk_fma_f32 v[136:137], v[124:125], v[166:167], v[136:137]
	v_pk_fma_f32 v[134:135], v[122:123], v[164:165], v[134:135]
	global_store_dwordx4 v[168:169], v[130:133], off nt
	global_store_dwordx4 v[168:169], v[134:137], off offset:16 nt

.Lepi_qup:
	s_lshl_b32 s9, s9, 8
	s_add_i32 s9, s9, s60
	s_lshl_b32 s78, s8, 8
	s_or_b32 s78, s78, s26
	s_mov_b32 s8, s9
	s_mul_i32 s9, s9, 0xc00
	s_mul_i32 s41, s78, 2
	s_add_i32 s9, s9, s41
	s_lshl_b32 s8, s8, 2
	s_add_u32 s74, s36, s8
	s_addc_u32 s75, s37, 0
	s_add_u32 s74, s74, 0x1100000
	s_addc_u32 s75, s75, 0
	v_lshlrev_b32_e32 v131, 2, v1
	global_load_dword v152, v131, s[74:75] offset:0
	global_load_dword v153, v131, s[74:75] offset:64
	global_load_dword v154, v131, s[74:75] offset:128
	global_load_dword v155, v131, s[74:75] offset:192
	global_load_dword v156, v131, s[74:75] offset:512
	global_load_dword v157, v131, s[74:75] offset:576
	global_load_dword v158, v131, s[74:75] offset:640
	global_load_dword v159, v131, s[74:75] offset:704
	s_add_u32 s46, s36, s9
	s_addc_u32 s47, s37, 0
	s_add_u32 s46, s46, 0x17600000
	s_addc_u32 s47, s47, 0
	v_mul_u32_u24_e32 v130, 0xc00, v1
	v_lshl_add_u32 v130, v176, 1, v130
	s_waitcnt vmcnt(0)
	v_fmamk_f32 v152, v152, 0x3b800000, v207
	v_fmamk_f32 v153, v153, 0x3b800000, v207
	v_fmamk_f32 v154, v154, 0x3b800000, v207
	v_fmamk_f32 v155, v155, 0x3b800000, v207
	v_fmamk_f32 v156, v156, 0x3b800000, v207
	v_fmamk_f32 v157, v157, 0x3b800000, v207
	v_fmamk_f32 v158, v158, 0x3b800000, v207
	v_fmamk_f32 v159, v159, 0x3b800000, v207
	v_rsq_f32_e32 v152, v152
	v_rsq_f32_e32 v153, v153
	v_rsq_f32_e32 v154, v154
	v_rsq_f32_e32 v155, v155
	v_rsq_f32_e32 v156, v156
	v_rsq_f32_e32 v157, v157
	v_rsq_f32_e32 v158, v158
	v_rsq_f32_e32 v159, v159
	v_mul_f32_e32 v160, v152, v126
	v_mul_f32_e32 v161, v152, v127
	v_mul_f32_e32 v162, v152, v128
	v_mul_f32_e32 v163, v152, v129
	v_mul_f32_e32 v164, v152, v122
	v_mul_f32_e32 v165, v152, v123
	v_mul_f32_e32 v166, v152, v124
	v_mul_f32_e32 v167, v152, v125
	v_cvt_pk_bf16_f32 v132, v160, v161
	v_cvt_pk_bf16_f32 v133, v162, v163
	v_cvt_pk_bf16_f32 v134, v164, v165
	v_cvt_pk_bf16_f32 v135, v166, v167
	global_store_dwordx4 v130, v[132:135], s[46:47]
	v_mul_f32_e32 v168, v152, v118
	v_mul_f32_e32 v169, v152, v119
	v_mul_f32_e32 v170, v152, v120
	v_mul_f32_e32 v171, v152, v121
	v_mul_f32_e32 v172, v152, v114
	v_mul_f32_e32 v173, v152, v115
	v_mul_f32_e32 v174, v152, v116
	v_mul_f32_e32 v175, v152, v117
	v_cvt_pk_bf16_f32 v180, v168, v169
	v_cvt_pk_bf16_f32 v181, v170, v171
	v_cvt_pk_bf16_f32 v182, v172, v173
	v_cvt_pk_bf16_f32 v183, v174, v175
	global_store_dwordx4 v130, v[180:183], s[46:47] offset:256
	v_mul_f32_e32 v160, v153, v110
	v_mul_f32_e32 v161, v153, v111
	v_mul_f32_e32 v162, v153, v112
	v_mul_f32_e32 v163, v153, v113
	v_mul_f32_e32 v164, v153, v106
	v_mul_f32_e32 v165, v153, v107
	v_mul_f32_e32 v166, v153, v108
	v_mul_f32_e32 v167, v153, v109
	v_cvt_pk_bf16_f32 v132, v160, v161
	v_cvt_pk_bf16_f32 v133, v162, v163
	v_cvt_pk_bf16_f32 v134, v164, v165
	v_cvt_pk_bf16_f32 v135, v166, v167
	s_add_u32 s46, s46, 0xc000
	s_addc_u32 s47, s47, 0
	global_store_dwordx4 v130, v[132:135], s[46:47]
	v_mul_f32_e32 v168, v153, v102
	v_mul_f32_e32 v169, v153, v103
	v_mul_f32_e32 v170, v153, v104
	v_mul_f32_e32 v171, v153, v105
	v_mul_f32_e32 v172, v153, v98
	v_mul_f32_e32 v173, v153, v99
	v_mul_f32_e32 v174, v153, v100
	v_mul_f32_e32 v175, v153, v101
	v_cvt_pk_bf16_f32 v180, v168, v169
	v_cvt_pk_bf16_f32 v181, v170, v171
	v_cvt_pk_bf16_f32 v182, v172, v173
	v_cvt_pk_bf16_f32 v183, v174, v175
	global_store_dwordx4 v130, v[180:183], s[46:47] offset:256
	v_mul_f32_e32 v160, v154, v94
	v_mul_f32_e32 v161, v154, v95
	v_mul_f32_e32 v162, v154, v96
	v_mul_f32_e32 v163, v154, v97
	v_mul_f32_e32 v164, v154, v90
	v_mul_f32_e32 v165, v154, v91
	v_mul_f32_e32 v166, v154, v92
	v_mul_f32_e32 v167, v154, v93
	v_cvt_pk_bf16_f32 v132, v160, v161
	v_cvt_pk_bf16_f32 v133, v162, v163
	v_cvt_pk_bf16_f32 v134, v164, v165
	v_cvt_pk_bf16_f32 v135, v166, v167
	s_add_u32 s46, s46, 0xc000
	s_addc_u32 s47, s47, 0
	global_store_dwordx4 v130, v[132:135], s[46:47]
	v_mul_f32_e32 v168, v154, v86
	v_mul_f32_e32 v169, v154, v87
	v_mul_f32_e32 v170, v154, v88
	v_mul_f32_e32 v171, v154, v89
	v_mul_f32_e32 v172, v154, v82
	v_mul_f32_e32 v173, v154, v83
	v_mul_f32_e32 v174, v154, v84
	v_mul_f32_e32 v175, v154, v85
	v_cvt_pk_bf16_f32 v180, v168, v169
	v_cvt_pk_bf16_f32 v181, v170, v171
	v_cvt_pk_bf16_f32 v182, v172, v173
	v_cvt_pk_bf16_f32 v183, v174, v175
	global_store_dwordx4 v130, v[180:183], s[46:47] offset:256
	v_mul_f32_e32 v160, v155, v78
	v_mul_f32_e32 v161, v155, v79
	v_mul_f32_e32 v162, v155, v80
	v_mul_f32_e32 v163, v155, v81
	v_mul_f32_e32 v164, v155, v74
	v_mul_f32_e32 v165, v155, v75
	v_mul_f32_e32 v166, v155, v76
	v_mul_f32_e32 v167, v155, v77
	v_cvt_pk_bf16_f32 v132, v160, v161
	v_cvt_pk_bf16_f32 v133, v162, v163
	v_cvt_pk_bf16_f32 v134, v164, v165
	v_cvt_pk_bf16_f32 v135, v166, v167
	s_add_u32 s46, s46, 0xc000
	s_addc_u32 s47, s47, 0
	global_store_dwordx4 v130, v[132:135], s[46:47]
	v_mul_f32_e32 v168, v155, v70
	v_mul_f32_e32 v169, v155, v71
	v_mul_f32_e32 v170, v155, v72
	v_mul_f32_e32 v171, v155, v73
	v_mul_f32_e32 v172, v155, v66
	v_mul_f32_e32 v173, v155, v67
	v_mul_f32_e32 v174, v155, v68
	v_mul_f32_e32 v175, v155, v69
	v_cvt_pk_bf16_f32 v180, v168, v169
	v_cvt_pk_bf16_f32 v181, v170, v171
	v_cvt_pk_bf16_f32 v182, v172, v173
	v_cvt_pk_bf16_f32 v183, v174, v175
	global_store_dwordx4 v130, v[180:183], s[46:47] offset:256
	v_mul_f32_e32 v160, v156, v62
	v_mul_f32_e32 v161, v156, v63
	v_mul_f32_e32 v162, v156, v64
	v_mul_f32_e32 v163, v156, v65
	v_mul_f32_e32 v164, v156, v58
	v_mul_f32_e32 v165, v156, v59
	v_mul_f32_e32 v166, v156, v60
	v_mul_f32_e32 v167, v156, v61
	v_cvt_pk_bf16_f32 v132, v160, v161
	v_cvt_pk_bf16_f32 v133, v162, v163
	v_cvt_pk_bf16_f32 v134, v164, v165
	v_cvt_pk_bf16_f32 v135, v166, v167
	s_add_u32 s46, s46, 0x3c000
	s_addc_u32 s47, s47, 0
	global_store_dwordx4 v130, v[132:135], s[46:47]
	v_mul_f32_e32 v168, v156, v54
	v_mul_f32_e32 v169, v156, v55
	v_mul_f32_e32 v170, v156, v56
	v_mul_f32_e32 v171, v156, v57
	v_mul_f32_e32 v172, v156, v50
	v_mul_f32_e32 v173, v156, v51
	v_mul_f32_e32 v174, v156, v52
	v_mul_f32_e32 v175, v156, v53
	v_cvt_pk_bf16_f32 v180, v168, v169
	v_cvt_pk_bf16_f32 v181, v170, v171
	v_cvt_pk_bf16_f32 v182, v172, v173
	v_cvt_pk_bf16_f32 v183, v174, v175
	global_store_dwordx4 v130, v[180:183], s[46:47] offset:256
	v_mul_f32_e32 v160, v157, v46
	v_mul_f32_e32 v161, v157, v47
	v_mul_f32_e32 v162, v157, v48
	v_mul_f32_e32 v163, v157, v49
	v_mul_f32_e32 v164, v157, v42
	v_mul_f32_e32 v165, v157, v43
	v_mul_f32_e32 v166, v157, v44
	v_mul_f32_e32 v167, v157, v45
	v_cvt_pk_bf16_f32 v132, v160, v161
	v_cvt_pk_bf16_f32 v133, v162, v163
	v_cvt_pk_bf16_f32 v134, v164, v165
	v_cvt_pk_bf16_f32 v135, v166, v167
	s_add_u32 s46, s46, 0xc000
	s_addc_u32 s47, s47, 0
	global_store_dwordx4 v130, v[132:135], s[46:47]
	v_mul_f32_e32 v168, v157, v38
	v_mul_f32_e32 v169, v157, v39
	v_mul_f32_e32 v170, v157, v40
	v_mul_f32_e32 v171, v157, v41
	v_mul_f32_e32 v172, v157, v34
	v_mul_f32_e32 v173, v157, v35
	v_mul_f32_e32 v174, v157, v36
	v_mul_f32_e32 v175, v157, v37
	v_cvt_pk_bf16_f32 v180, v168, v169
	v_cvt_pk_bf16_f32 v181, v170, v171
	v_cvt_pk_bf16_f32 v182, v172, v173
	v_cvt_pk_bf16_f32 v183, v174, v175
	global_store_dwordx4 v130, v[180:183], s[46:47] offset:256
	v_mul_f32_e32 v160, v158, v30
	v_mul_f32_e32 v161, v158, v31
	v_mul_f32_e32 v162, v158, v32
	v_mul_f32_e32 v163, v158, v33
	v_mul_f32_e32 v164, v158, v26
	v_mul_f32_e32 v165, v158, v27
	v_mul_f32_e32 v166, v158, v28
	v_mul_f32_e32 v167, v158, v29
	v_cvt_pk_bf16_f32 v132, v160, v161
	v_cvt_pk_bf16_f32 v133, v162, v163
	v_cvt_pk_bf16_f32 v134, v164, v165
	v_cvt_pk_bf16_f32 v135, v166, v167
	s_add_u32 s46, s46, 0xc000
	s_addc_u32 s47, s47, 0
	global_store_dwordx4 v130, v[132:135], s[46:47]
	v_mul_f32_e32 v168, v158, v22
	v_mul_f32_e32 v169, v158, v23
	v_mul_f32_e32 v170, v158, v24
	v_mul_f32_e32 v171, v158, v25
	v_mul_f32_e32 v172, v158, v18
	v_mul_f32_e32 v173, v158, v19
	v_mul_f32_e32 v174, v158, v20
	v_mul_f32_e32 v175, v158, v21
	v_cvt_pk_bf16_f32 v180, v168, v169
	v_cvt_pk_bf16_f32 v181, v170, v171
	v_cvt_pk_bf16_f32 v182, v172, v173
	v_cvt_pk_bf16_f32 v183, v174, v175
	global_store_dwordx4 v130, v[180:183], s[46:47] offset:256
	v_mul_f32_e32 v160, v159, v14
	v_mul_f32_e32 v161, v159, v15
	v_mul_f32_e32 v162, v159, v16
	v_mul_f32_e32 v163, v159, v17
	v_mul_f32_e32 v164, v159, v10
	v_mul_f32_e32 v165, v159, v11
	v_mul_f32_e32 v166, v159, v12
	v_mul_f32_e32 v167, v159, v13
	v_cvt_pk_bf16_f32 v132, v160, v161
	v_cvt_pk_bf16_f32 v133, v162, v163
	v_cvt_pk_bf16_f32 v134, v164, v165
	v_cvt_pk_bf16_f32 v135, v166, v167
	s_add_u32 s46, s46, 0xc000
	s_addc_u32 s47, s47, 0
	global_store_dwordx4 v130, v[132:135], s[46:47]
	v_mul_f32_e32 v168, v159, v6
	v_mul_f32_e32 v169, v159, v7
	v_mul_f32_e32 v170, v159, v8
	v_mul_f32_e32 v171, v159, v9
	v_mul_f32_e32 v172, v159, v2
	v_mul_f32_e32 v173, v159, v3
	v_mul_f32_e32 v174, v159, v4
	v_mul_f32_e32 v175, v159, v5
	v_cvt_pk_bf16_f32 v180, v168, v169
	v_cvt_pk_bf16_f32 v181, v170, v171
	v_cvt_pk_bf16_f32 v182, v172, v173
	v_cvt_pk_bf16_f32 v183, v174, v175
	global_store_dwordx4 v130, v[180:183], s[46:47] offset:256
	s_branch .LBB0_1251
.Lepi_kup:
	s_lshl_b32 s9, s9, 8
	s_add_i32 s9, s9, s60
	s_lshl_b32 s78, s8, 8
	s_or_b32 s78, s78, s26
	s_lshl_b32 s8, s9, 2
	s_add_u32 s74, s36, s8
	s_addc_u32 s75, s37, 0
	s_add_u32 s74, s74, 0x1140000
	s_addc_u32 s75, s75, 0
	v_lshlrev_b32_e32 v132, 2, v1
	global_load_dword v152, v132, s[74:75] offset:0
	global_load_dword v153, v132, s[74:75] offset:64
	global_load_dword v154, v132, s[74:75] offset:128
	global_load_dword v155, v132, s[74:75] offset:192
	global_load_dword v156, v132, s[74:75] offset:512
	global_load_dword v157, v132, s[74:75] offset:576
	global_load_dword v158, v132, s[74:75] offset:640
	global_load_dword v159, v132, s[74:75] offset:704
	s_lshr_b32 s8, s9, 11
	s_lshl_b32 s8, s8, 4
	s_lshr_b32 s41, s78, 6
	s_add_i32 s8, s8, s41
	s_lshl_b32 s8, s8, 18
	s_and_b32 s41, s9, 0x7ff
	s_lshl_b32 s41, s41, 7
	s_add_i32 s8, s8, s41
	s_and_b32 s41, s78, 63
	s_lshl_b32 s41, s41, 1
	s_add_i32 s8, s8, s41
	s_add_u32 s46, s36, s8
	s_addc_u32 s47, s37, 0
	s_add_u32 s46, s46, 0x3600000
	s_addc_u32 s47, s47, 0
	s_lshl_b32 s8, s9, 6
	s_lshr_b32 s41, s78, 6
	s_lshl_b32 s41, s41, 2
	s_add_i32 s8, s8, s41
	s_add_u32 s38, s36, s8
	s_addc_u32 s39, s37, 0
	s_add_u32 s38, s38, 0x900000
	s_addc_u32 s39, s39, 0
	v_lshlrev_b32_e32 v130, 7, v1
	v_lshl_add_u32 v130, v176, 1, v130
	v_add_u32_e32 v131, 0x80000, v130
	v_lshlrev_b32_e32 v133, 6, v1
	v_cmp_eq_u32_e64 s[68:69], 0, v176
	s_waitcnt vmcnt(0)
	v_fmamk_f32 v152, v152, 0x3c000000, v207
	v_fmamk_f32 v153, v153, 0x3c000000, v207
	v_fmamk_f32 v154, v154, 0x3c000000, v207
	v_fmamk_f32 v155, v155, 0x3c000000, v207
	v_fmamk_f32 v156, v156, 0x3c000000, v207
	v_fmamk_f32 v157, v157, 0x3c000000, v207
	v_fmamk_f32 v158, v158, 0x3c000000, v207
	v_fmamk_f32 v159, v159, 0x3c000000, v207
	v_rsq_f32_e32 v152, v152
	v_rsq_f32_e32 v153, v153
	v_rsq_f32_e32 v154, v154
	v_rsq_f32_e32 v155, v155
	v_rsq_f32_e32 v156, v156
	v_rsq_f32_e32 v157, v157
	v_rsq_f32_e32 v158, v158
	v_rsq_f32_e32 v159, v159
	v_mul_f32_e32 v160, v152, v126
	v_mul_f32_e32 v161, v152, v127
	v_mul_f32_e32 v162, v152, v128
	v_mul_f32_e32 v163, v152, v129
	v_mul_f32_e32 v164, v152, v122
	v_mul_f32_e32 v165, v152, v123
	v_mul_f32_e32 v166, v152, v124
	v_mul_f32_e32 v167, v152, v125
	v_mul_f32_e32 v184, v161, v161
	v_mul_f32_e32 v185, v163, v163
	v_mul_f32_e32 v186, v165, v165
	v_mul_f32_e32 v187, v167, v167
	v_fmac_f32_e32 v184, v160, v160
	v_fmac_f32_e32 v185, v162, v162
	v_fmac_f32_e32 v186, v164, v164
	v_fmac_f32_e32 v187, v166, v166
	v_add_f32_e32 v184, v184, v185
	v_add_f32_e32 v184, v186, v184
	v_add_f32_e32 v192, v187, v184
	v_cvt_pk_bf16_f32 v134, v160, v161
	v_cvt_pk_bf16_f32 v135, v162, v163
	v_cvt_pk_bf16_f32 v136, v164, v165
	v_cvt_pk_bf16_f32 v137, v166, v167
	v_mov_b32_e32 v193, v192
	global_store_dwordx4 v130, v[134:137], s[46:47]
	s_nop 1
	v_permlane16_swap_b32_e32 v192, v193
	v_add_f32_e32 v192, v192, v193
	v_mov_b32_e32 v193, v192
	s_nop 1
	v_permlane32_swap_b32_e32 v192, v193
	v_add_f32_e32 v192, v192, v193
	s_mov_b64 s[74:75], exec
	s_and_b64 exec, exec, s[68:69]
	global_atomic_add_f32 v133, v192, s[38:39]
	s_mov_b64 exec, s[74:75]
	v_mul_f32_e32 v168, v152, v118
	v_mul_f32_e32 v169, v152, v119
	v_mul_f32_e32 v170, v152, v120
	v_mul_f32_e32 v171, v152, v121
	v_mul_f32_e32 v172, v152, v114
	v_mul_f32_e32 v173, v152, v115
	v_mul_f32_e32 v174, v152, v116
	v_mul_f32_e32 v175, v152, v117
	v_mul_f32_e32 v188, v169, v169
	v_mul_f32_e32 v189, v171, v171
	v_mul_f32_e32 v190, v173, v173
	v_mul_f32_e32 v191, v175, v175
	v_fmac_f32_e32 v188, v168, v168
	v_fmac_f32_e32 v189, v170, v170
	v_fmac_f32_e32 v190, v172, v172
	v_fmac_f32_e32 v191, v174, v174
	v_add_f32_e32 v188, v188, v189
	v_add_f32_e32 v188, v190, v188
	v_add_f32_e32 v194, v191, v188
	v_cvt_pk_bf16_f32 v180, v168, v169
	v_cvt_pk_bf16_f32 v181, v170, v171
	v_cvt_pk_bf16_f32 v182, v172, v173
	v_cvt_pk_bf16_f32 v183, v174, v175
	v_mov_b32_e32 v195, v194
	global_store_dwordx4 v131, v[180:183], s[46:47]
	s_nop 1
	v_permlane16_swap_b32_e32 v194, v195
	v_add_f32_e32 v194, v194, v195
	v_mov_b32_e32 v195, v194
	s_nop 1
	v_permlane32_swap_b32_e32 v194, v195
	v_add_f32_e32 v194, v194, v195
	s_mov_b64 s[74:75], exec
	s_and_b64 exec, exec, s[68:69]
	global_atomic_add_f32 v133, v194, s[38:39] offset:8
	s_mov_b64 exec, s[74:75]
	v_mul_f32_e32 v160, v153, v110
	v_mul_f32_e32 v161, v153, v111
	v_mul_f32_e32 v162, v153, v112
	v_mul_f32_e32 v163, v153, v113
	v_mul_f32_e32 v164, v153, v106
	v_mul_f32_e32 v165, v153, v107
	v_mul_f32_e32 v166, v153, v108
	v_mul_f32_e32 v167, v153, v109
	v_mul_f32_e32 v184, v161, v161
	v_mul_f32_e32 v185, v163, v163
	v_mul_f32_e32 v186, v165, v165
	v_mul_f32_e32 v187, v167, v167
	v_fmac_f32_e32 v184, v160, v160
	v_fmac_f32_e32 v185, v162, v162
	v_fmac_f32_e32 v186, v164, v164
	v_fmac_f32_e32 v187, v166, v166
	v_add_f32_e32 v184, v184, v185
	v_add_f32_e32 v184, v186, v184
	v_add_f32_e32 v192, v187, v184
	v_cvt_pk_bf16_f32 v134, v160, v161
	v_cvt_pk_bf16_f32 v135, v162, v163
	v_cvt_pk_bf16_f32 v136, v164, v165
	v_cvt_pk_bf16_f32 v137, v166, v167
	v_mov_b32_e32 v193, v192
	s_add_u32 s46, s46, 0x800
	s_addc_u32 s47, s47, 0
	global_store_dwordx4 v130, v[134:137], s[46:47]
	s_nop 1
	v_permlane16_swap_b32_e32 v192, v193
	v_add_f32_e32 v192, v192, v193
	v_mov_b32_e32 v193, v192
	s_add_u32 s38, s38, 0x400
	s_addc_u32 s39, s39, 0
	s_nop 1
	v_permlane32_swap_b32_e32 v192, v193
	v_add_f32_e32 v192, v192, v193
	s_mov_b64 s[74:75], exec
	s_and_b64 exec, exec, s[68:69]
	global_atomic_add_f32 v133, v192, s[38:39]
	s_mov_b64 exec, s[74:75]
	v_mul_f32_e32 v168, v153, v102
	v_mul_f32_e32 v169, v153, v103
	v_mul_f32_e32 v170, v153, v104
	v_mul_f32_e32 v171, v153, v105
	v_mul_f32_e32 v172, v153, v98
	v_mul_f32_e32 v173, v153, v99
	v_mul_f32_e32 v174, v153, v100
	v_mul_f32_e32 v175, v153, v101
	v_mul_f32_e32 v188, v169, v169
	v_mul_f32_e32 v189, v171, v171
	v_mul_f32_e32 v190, v173, v173
	v_mul_f32_e32 v191, v175, v175
	v_fmac_f32_e32 v188, v168, v168
	v_fmac_f32_e32 v189, v170, v170
	v_fmac_f32_e32 v190, v172, v172
	v_fmac_f32_e32 v191, v174, v174
	v_add_f32_e32 v188, v188, v189
	v_add_f32_e32 v188, v190, v188
	v_add_f32_e32 v194, v191, v188
	v_cvt_pk_bf16_f32 v180, v168, v169
	v_cvt_pk_bf16_f32 v181, v170, v171
	v_cvt_pk_bf16_f32 v182, v172, v173
	v_cvt_pk_bf16_f32 v183, v174, v175
	v_mov_b32_e32 v195, v194
	global_store_dwordx4 v131, v[180:183], s[46:47]
	s_nop 1
	v_permlane16_swap_b32_e32 v194, v195
	v_add_f32_e32 v194, v194, v195
	v_mov_b32_e32 v195, v194
	s_nop 1
	v_permlane32_swap_b32_e32 v194, v195
	v_add_f32_e32 v194, v194, v195
	s_mov_b64 s[74:75], exec
	s_and_b64 exec, exec, s[68:69]
	global_atomic_add_f32 v133, v194, s[38:39] offset:8
	s_mov_b64 exec, s[74:75]
	v_mul_f32_e32 v160, v154, v94
	v_mul_f32_e32 v161, v154, v95
	v_mul_f32_e32 v162, v154, v96
	v_mul_f32_e32 v163, v154, v97
	v_mul_f32_e32 v164, v154, v90
	v_mul_f32_e32 v165, v154, v91
	v_mul_f32_e32 v166, v154, v92
	v_mul_f32_e32 v167, v154, v93
	v_mul_f32_e32 v184, v161, v161
	v_mul_f32_e32 v185, v163, v163
	v_mul_f32_e32 v186, v165, v165
	v_mul_f32_e32 v187, v167, v167
	v_fmac_f32_e32 v184, v160, v160
	v_fmac_f32_e32 v185, v162, v162
	v_fmac_f32_e32 v186, v164, v164
	v_fmac_f32_e32 v187, v166, v166
	v_add_f32_e32 v184, v184, v185
	v_add_f32_e32 v184, v186, v184
	v_add_f32_e32 v192, v187, v184
	v_cvt_pk_bf16_f32 v134, v160, v161
	v_cvt_pk_bf16_f32 v135, v162, v163
	v_cvt_pk_bf16_f32 v136, v164, v165
	v_cvt_pk_bf16_f32 v137, v166, v167
	v_mov_b32_e32 v193, v192
	s_add_u32 s46, s46, 0x800
	s_addc_u32 s47, s47, 0
	global_store_dwordx4 v130, v[134:137], s[46:47]
	s_nop 1
	v_permlane16_swap_b32_e32 v192, v193
	v_add_f32_e32 v192, v192, v193
	v_mov_b32_e32 v193, v192
	s_add_u32 s38, s38, 0x400
	s_addc_u32 s39, s39, 0
	s_nop 1
	v_permlane32_swap_b32_e32 v192, v193
	v_add_f32_e32 v192, v192, v193
	s_mov_b64 s[74:75], exec
	s_and_b64 exec, exec, s[68:69]
	global_atomic_add_f32 v133, v192, s[38:39]
	s_mov_b64 exec, s[74:75]
	v_mul_f32_e32 v168, v154, v86
	v_mul_f32_e32 v169, v154, v87
	v_mul_f32_e32 v170, v154, v88
	v_mul_f32_e32 v171, v154, v89
	v_mul_f32_e32 v172, v154, v82
	v_mul_f32_e32 v173, v154, v83
	v_mul_f32_e32 v174, v154, v84
	v_mul_f32_e32 v175, v154, v85
	v_mul_f32_e32 v188, v169, v169
	v_mul_f32_e32 v189, v171, v171
	v_mul_f32_e32 v190, v173, v173
	v_mul_f32_e32 v191, v175, v175
	v_fmac_f32_e32 v188, v168, v168
	v_fmac_f32_e32 v189, v170, v170
	v_fmac_f32_e32 v190, v172, v172
	v_fmac_f32_e32 v191, v174, v174
	v_add_f32_e32 v188, v188, v189
	v_add_f32_e32 v188, v190, v188
	v_add_f32_e32 v194, v191, v188
	v_cvt_pk_bf16_f32 v180, v168, v169
	v_cvt_pk_bf16_f32 v181, v170, v171
	v_cvt_pk_bf16_f32 v182, v172, v173
	v_cvt_pk_bf16_f32 v183, v174, v175
	v_mov_b32_e32 v195, v194
	global_store_dwordx4 v131, v[180:183], s[46:47]
	s_nop 1
	v_permlane16_swap_b32_e32 v194, v195
	v_add_f32_e32 v194, v194, v195
	v_mov_b32_e32 v195, v194
	s_nop 1
	v_permlane32_swap_b32_e32 v194, v195
	v_add_f32_e32 v194, v194, v195
	s_mov_b64 s[74:75], exec
	s_and_b64 exec, exec, s[68:69]
	global_atomic_add_f32 v133, v194, s[38:39] offset:8
	s_mov_b64 exec, s[74:75]
	v_mul_f32_e32 v160, v155, v78
	v_mul_f32_e32 v161, v155, v79
	v_mul_f32_e32 v162, v155, v80
	v_mul_f32_e32 v163, v155, v81
	v_mul_f32_e32 v164, v155, v74
	v_mul_f32_e32 v165, v155, v75
	v_mul_f32_e32 v166, v155, v76
	v_mul_f32_e32 v167, v155, v77
	v_mul_f32_e32 v184, v161, v161
	v_mul_f32_e32 v185, v163, v163
	v_mul_f32_e32 v186, v165, v165
	v_mul_f32_e32 v187, v167, v167
	v_fmac_f32_e32 v184, v160, v160
	v_fmac_f32_e32 v185, v162, v162
	v_fmac_f32_e32 v186, v164, v164
	v_fmac_f32_e32 v187, v166, v166
	v_add_f32_e32 v184, v184, v185
	v_add_f32_e32 v184, v186, v184
	v_add_f32_e32 v192, v187, v184
	v_cvt_pk_bf16_f32 v134, v160, v161
	v_cvt_pk_bf16_f32 v135, v162, v163
	v_cvt_pk_bf16_f32 v136, v164, v165
	v_cvt_pk_bf16_f32 v137, v166, v167
	v_mov_b32_e32 v193, v192
	s_add_u32 s46, s46, 0x800
	s_addc_u32 s47, s47, 0
	global_store_dwordx4 v130, v[134:137], s[46:47]
	s_nop 1
	v_permlane16_swap_b32_e32 v192, v193
	v_add_f32_e32 v192, v192, v193
	v_mov_b32_e32 v193, v192
	s_add_u32 s38, s38, 0x400
	s_addc_u32 s39, s39, 0
	s_nop 1
	v_permlane32_swap_b32_e32 v192, v193
	v_add_f32_e32 v192, v192, v193
	s_mov_b64 s[74:75], exec
	s_and_b64 exec, exec, s[68:69]
	global_atomic_add_f32 v133, v192, s[38:39]
	s_mov_b64 exec, s[74:75]
	v_mul_f32_e32 v168, v155, v70
	v_mul_f32_e32 v169, v155, v71
	v_mul_f32_e32 v170, v155, v72
	v_mul_f32_e32 v171, v155, v73
	v_mul_f32_e32 v172, v155, v66
	v_mul_f32_e32 v173, v155, v67
	v_mul_f32_e32 v174, v155, v68
	v_mul_f32_e32 v175, v155, v69
	v_mul_f32_e32 v188, v169, v169
	v_mul_f32_e32 v189, v171, v171
	v_mul_f32_e32 v190, v173, v173
	v_mul_f32_e32 v191, v175, v175
	v_fmac_f32_e32 v188, v168, v168
	v_fmac_f32_e32 v189, v170, v170
	v_fmac_f32_e32 v190, v172, v172
	v_fmac_f32_e32 v191, v174, v174
	v_add_f32_e32 v188, v188, v189
	v_add_f32_e32 v188, v190, v188
	v_add_f32_e32 v194, v191, v188
	v_cvt_pk_bf16_f32 v180, v168, v169
	v_cvt_pk_bf16_f32 v181, v170, v171
	v_cvt_pk_bf16_f32 v182, v172, v173
	v_cvt_pk_bf16_f32 v183, v174, v175
	v_mov_b32_e32 v195, v194
	global_store_dwordx4 v131, v[180:183], s[46:47]
	s_nop 1
	v_permlane16_swap_b32_e32 v194, v195
	v_add_f32_e32 v194, v194, v195
	v_mov_b32_e32 v195, v194
	s_nop 1
	v_permlane32_swap_b32_e32 v194, v195
	v_add_f32_e32 v194, v194, v195
	s_mov_b64 s[74:75], exec
	s_and_b64 exec, exec, s[68:69]
	global_atomic_add_f32 v133, v194, s[38:39] offset:8
	s_mov_b64 exec, s[74:75]
	v_mul_f32_e32 v160, v156, v62
	v_mul_f32_e32 v161, v156, v63
	v_mul_f32_e32 v162, v156, v64
	v_mul_f32_e32 v163, v156, v65
	v_mul_f32_e32 v164, v156, v58
	v_mul_f32_e32 v165, v156, v59
	v_mul_f32_e32 v166, v156, v60
	v_mul_f32_e32 v167, v156, v61
	v_mul_f32_e32 v184, v161, v161
	v_mul_f32_e32 v185, v163, v163
	v_mul_f32_e32 v186, v165, v165
	v_mul_f32_e32 v187, v167, v167
	v_fmac_f32_e32 v184, v160, v160
	v_fmac_f32_e32 v185, v162, v162
	v_fmac_f32_e32 v186, v164, v164
	v_fmac_f32_e32 v187, v166, v166
	v_add_f32_e32 v184, v184, v185
	v_add_f32_e32 v184, v186, v184
	v_add_f32_e32 v192, v187, v184
	v_cvt_pk_bf16_f32 v134, v160, v161
	v_cvt_pk_bf16_f32 v135, v162, v163
	v_cvt_pk_bf16_f32 v136, v164, v165
	v_cvt_pk_bf16_f32 v137, v166, v167
	v_mov_b32_e32 v193, v192
	s_add_u32 s46, s46, 0x2800
	s_addc_u32 s47, s47, 0
	global_store_dwordx4 v130, v[134:137], s[46:47]
	s_nop 1
	v_permlane16_swap_b32_e32 v192, v193
	v_add_f32_e32 v192, v192, v193
	v_mov_b32_e32 v193, v192
	s_add_u32 s38, s38, 0x1400
	s_addc_u32 s39, s39, 0
	s_nop 1
	v_permlane32_swap_b32_e32 v192, v193
	v_add_f32_e32 v192, v192, v193
	s_mov_b64 s[74:75], exec
	s_and_b64 exec, exec, s[68:69]
	global_atomic_add_f32 v133, v192, s[38:39]
	s_mov_b64 exec, s[74:75]
	v_mul_f32_e32 v168, v156, v54
	v_mul_f32_e32 v169, v156, v55
	v_mul_f32_e32 v170, v156, v56
	v_mul_f32_e32 v171, v156, v57
	v_mul_f32_e32 v172, v156, v50
	v_mul_f32_e32 v173, v156, v51
	v_mul_f32_e32 v174, v156, v52
	v_mul_f32_e32 v175, v156, v53
	v_mul_f32_e32 v188, v169, v169
	v_mul_f32_e32 v189, v171, v171
	v_mul_f32_e32 v190, v173, v173
	v_mul_f32_e32 v191, v175, v175
	v_fmac_f32_e32 v188, v168, v168
	v_fmac_f32_e32 v189, v170, v170
	v_fmac_f32_e32 v190, v172, v172
	v_fmac_f32_e32 v191, v174, v174
	v_add_f32_e32 v188, v188, v189
	v_add_f32_e32 v188, v190, v188
	v_add_f32_e32 v194, v191, v188
	v_cvt_pk_bf16_f32 v180, v168, v169
	v_cvt_pk_bf16_f32 v181, v170, v171
	v_cvt_pk_bf16_f32 v182, v172, v173
	v_cvt_pk_bf16_f32 v183, v174, v175
	v_mov_b32_e32 v195, v194
	global_store_dwordx4 v131, v[180:183], s[46:47]
	s_nop 1
	v_permlane16_swap_b32_e32 v194, v195
	v_add_f32_e32 v194, v194, v195
	v_mov_b32_e32 v195, v194
	s_nop 1
	v_permlane32_swap_b32_e32 v194, v195
	v_add_f32_e32 v194, v194, v195
	s_mov_b64 s[74:75], exec
	s_and_b64 exec, exec, s[68:69]
	global_atomic_add_f32 v133, v194, s[38:39] offset:8
	s_mov_b64 exec, s[74:75]
	v_mul_f32_e32 v160, v157, v46
	v_mul_f32_e32 v161, v157, v47
	v_mul_f32_e32 v162, v157, v48
	v_mul_f32_e32 v163, v157, v49
	v_mul_f32_e32 v164, v157, v42
	v_mul_f32_e32 v165, v157, v43
	v_mul_f32_e32 v166, v157, v44
	v_mul_f32_e32 v167, v157, v45
	v_mul_f32_e32 v184, v161, v161
	v_mul_f32_e32 v185, v163, v163
	v_mul_f32_e32 v186, v165, v165
	v_mul_f32_e32 v187, v167, v167
	v_fmac_f32_e32 v184, v160, v160
	v_fmac_f32_e32 v185, v162, v162
	v_fmac_f32_e32 v186, v164, v164
	v_fmac_f32_e32 v187, v166, v166
	v_add_f32_e32 v184, v184, v185
	v_add_f32_e32 v184, v186, v184
	v_add_f32_e32 v192, v187, v184
	v_cvt_pk_bf16_f32 v134, v160, v161
	v_cvt_pk_bf16_f32 v135, v162, v163
	v_cvt_pk_bf16_f32 v136, v164, v165
	v_cvt_pk_bf16_f32 v137, v166, v167
	v_mov_b32_e32 v193, v192
	s_add_u32 s46, s46, 0x800
	s_addc_u32 s47, s47, 0
	global_store_dwordx4 v130, v[134:137], s[46:47]
	s_nop 1
	v_permlane16_swap_b32_e32 v192, v193
	v_add_f32_e32 v192, v192, v193
	v_mov_b32_e32 v193, v192
	s_add_u32 s38, s38, 0x400
	s_addc_u32 s39, s39, 0
	s_nop 1
	v_permlane32_swap_b32_e32 v192, v193
	v_add_f32_e32 v192, v192, v193
	s_mov_b64 s[74:75], exec
	s_and_b64 exec, exec, s[68:69]
	global_atomic_add_f32 v133, v192, s[38:39]
	s_mov_b64 exec, s[74:75]
	v_mul_f32_e32 v168, v157, v38
	v_mul_f32_e32 v169, v157, v39
	v_mul_f32_e32 v170, v157, v40
	v_mul_f32_e32 v171, v157, v41
	v_mul_f32_e32 v172, v157, v34
	v_mul_f32_e32 v173, v157, v35
	v_mul_f32_e32 v174, v157, v36
	v_mul_f32_e32 v175, v157, v37
	v_mul_f32_e32 v188, v169, v169
	v_mul_f32_e32 v189, v171, v171
	v_mul_f32_e32 v190, v173, v173
	v_mul_f32_e32 v191, v175, v175
	v_fmac_f32_e32 v188, v168, v168
	v_fmac_f32_e32 v189, v170, v170
	v_fmac_f32_e32 v190, v172, v172
	v_fmac_f32_e32 v191, v174, v174
	v_add_f32_e32 v188, v188, v189
	v_add_f32_e32 v188, v190, v188
	v_add_f32_e32 v194, v191, v188
	v_cvt_pk_bf16_f32 v180, v168, v169
	v_cvt_pk_bf16_f32 v181, v170, v171
	v_cvt_pk_bf16_f32 v182, v172, v173
	v_cvt_pk_bf16_f32 v183, v174, v175
	v_mov_b32_e32 v195, v194
	global_store_dwordx4 v131, v[180:183], s[46:47]
	s_nop 1
	v_permlane16_swap_b32_e32 v194, v195
	v_add_f32_e32 v194, v194, v195
	v_mov_b32_e32 v195, v194
	s_nop 1
	v_permlane32_swap_b32_e32 v194, v195
	v_add_f32_e32 v194, v194, v195
	s_mov_b64 s[74:75], exec
	s_and_b64 exec, exec, s[68:69]
	global_atomic_add_f32 v133, v194, s[38:39] offset:8
	s_mov_b64 exec, s[74:75]
	v_mul_f32_e32 v160, v158, v30
	v_mul_f32_e32 v161, v158, v31
	v_mul_f32_e32 v162, v158, v32
	v_mul_f32_e32 v163, v158, v33
	v_mul_f32_e32 v164, v158, v26
	v_mul_f32_e32 v165, v158, v27
	v_mul_f32_e32 v166, v158, v28
	v_mul_f32_e32 v167, v158, v29
	v_mul_f32_e32 v184, v161, v161
	v_mul_f32_e32 v185, v163, v163
	v_mul_f32_e32 v186, v165, v165
	v_mul_f32_e32 v187, v167, v167
	v_fmac_f32_e32 v184, v160, v160
	v_fmac_f32_e32 v185, v162, v162
	v_fmac_f32_e32 v186, v164, v164
	v_fmac_f32_e32 v187, v166, v166
	v_add_f32_e32 v184, v184, v185
	v_add_f32_e32 v184, v186, v184
	v_add_f32_e32 v192, v187, v184
	v_cvt_pk_bf16_f32 v134, v160, v161
	v_cvt_pk_bf16_f32 v135, v162, v163
	v_cvt_pk_bf16_f32 v136, v164, v165
	v_cvt_pk_bf16_f32 v137, v166, v167
	v_mov_b32_e32 v193, v192
	s_add_u32 s46, s46, 0x800
	s_addc_u32 s47, s47, 0
	global_store_dwordx4 v130, v[134:137], s[46:47]
	s_nop 1
	v_permlane16_swap_b32_e32 v192, v193
	v_add_f32_e32 v192, v192, v193
	v_mov_b32_e32 v193, v192
	s_add_u32 s38, s38, 0x400
	s_addc_u32 s39, s39, 0
	s_nop 1
	v_permlane32_swap_b32_e32 v192, v193
	v_add_f32_e32 v192, v192, v193
	s_mov_b64 s[74:75], exec
	s_and_b64 exec, exec, s[68:69]
	global_atomic_add_f32 v133, v192, s[38:39]
	s_mov_b64 exec, s[74:75]
	v_mul_f32_e32 v168, v158, v22
	v_mul_f32_e32 v169, v158, v23
	v_mul_f32_e32 v170, v158, v24
	v_mul_f32_e32 v171, v158, v25
	v_mul_f32_e32 v172, v158, v18
	v_mul_f32_e32 v173, v158, v19
	v_mul_f32_e32 v174, v158, v20
	v_mul_f32_e32 v175, v158, v21
	v_mul_f32_e32 v188, v169, v169
	v_mul_f32_e32 v189, v171, v171
	v_mul_f32_e32 v190, v173, v173
	v_mul_f32_e32 v191, v175, v175
	v_fmac_f32_e32 v188, v168, v168
	v_fmac_f32_e32 v189, v170, v170
	v_fmac_f32_e32 v190, v172, v172
	v_fmac_f32_e32 v191, v174, v174
	v_add_f32_e32 v188, v188, v189
	v_add_f32_e32 v188, v190, v188
	v_add_f32_e32 v194, v191, v188
	v_cvt_pk_bf16_f32 v180, v168, v169
	v_cvt_pk_bf16_f32 v181, v170, v171
	v_cvt_pk_bf16_f32 v182, v172, v173
	v_cvt_pk_bf16_f32 v183, v174, v175
	v_mov_b32_e32 v195, v194
	global_store_dwordx4 v131, v[180:183], s[46:47]
	s_nop 1
	v_permlane16_swap_b32_e32 v194, v195
	v_add_f32_e32 v194, v194, v195
	v_mov_b32_e32 v195, v194
	s_nop 1
	v_permlane32_swap_b32_e32 v194, v195
	v_add_f32_e32 v194, v194, v195
	s_mov_b64 s[74:75], exec
	s_and_b64 exec, exec, s[68:69]
	global_atomic_add_f32 v133, v194, s[38:39] offset:8
	s_mov_b64 exec, s[74:75]
	v_mul_f32_e32 v160, v159, v14
	v_mul_f32_e32 v161, v159, v15
	v_mul_f32_e32 v162, v159, v16
	v_mul_f32_e32 v163, v159, v17
	v_mul_f32_e32 v164, v159, v10
	v_mul_f32_e32 v165, v159, v11
	v_mul_f32_e32 v166, v159, v12
	v_mul_f32_e32 v167, v159, v13
	v_mul_f32_e32 v184, v161, v161
	v_mul_f32_e32 v185, v163, v163
	v_mul_f32_e32 v186, v165, v165
	v_mul_f32_e32 v187, v167, v167
	v_fmac_f32_e32 v184, v160, v160
	v_fmac_f32_e32 v185, v162, v162
	v_fmac_f32_e32 v186, v164, v164
	v_fmac_f32_e32 v187, v166, v166
	v_add_f32_e32 v184, v184, v185
	v_add_f32_e32 v184, v186, v184
	v_add_f32_e32 v192, v187, v184
	v_cvt_pk_bf16_f32 v134, v160, v161
	v_cvt_pk_bf16_f32 v135, v162, v163
	v_cvt_pk_bf16_f32 v136, v164, v165
	v_cvt_pk_bf16_f32 v137, v166, v167
	v_mov_b32_e32 v193, v192
	s_add_u32 s46, s46, 0x800
	s_addc_u32 s47, s47, 0
	global_store_dwordx4 v130, v[134:137], s[46:47]
	s_nop 1
	v_permlane16_swap_b32_e32 v192, v193
	v_add_f32_e32 v192, v192, v193
	v_mov_b32_e32 v193, v192
	s_add_u32 s38, s38, 0x400
	s_addc_u32 s39, s39, 0
	s_nop 1
	v_permlane32_swap_b32_e32 v192, v193
	v_add_f32_e32 v192, v192, v193
	s_mov_b64 s[74:75], exec
	s_and_b64 exec, exec, s[68:69]
	global_atomic_add_f32 v133, v192, s[38:39]
	s_mov_b64 exec, s[74:75]
	v_mul_f32_e32 v168, v159, v6
	v_mul_f32_e32 v169, v159, v7
	v_mul_f32_e32 v170, v159, v8
	v_mul_f32_e32 v171, v159, v9
	v_mul_f32_e32 v172, v159, v2
	v_mul_f32_e32 v173, v159, v3
	v_mul_f32_e32 v174, v159, v4
	v_mul_f32_e32 v175, v159, v5
	v_mul_f32_e32 v188, v169, v169
	v_mul_f32_e32 v189, v171, v171
	v_mul_f32_e32 v190, v173, v173
	v_mul_f32_e32 v191, v175, v175
	v_fmac_f32_e32 v188, v168, v168
	v_fmac_f32_e32 v189, v170, v170
	v_fmac_f32_e32 v190, v172, v172
	v_fmac_f32_e32 v191, v174, v174
	v_add_f32_e32 v188, v188, v189
	v_add_f32_e32 v188, v190, v188
	v_add_f32_e32 v194, v191, v188
	v_cvt_pk_bf16_f32 v180, v168, v169
	v_cvt_pk_bf16_f32 v181, v170, v171
	v_cvt_pk_bf16_f32 v182, v172, v173
	v_cvt_pk_bf16_f32 v183, v174, v175
	v_mov_b32_e32 v195, v194
	global_store_dwordx4 v131, v[180:183], s[46:47]
	s_nop 1
	v_permlane16_swap_b32_e32 v194, v195
	v_add_f32_e32 v194, v194, v195
	v_mov_b32_e32 v195, v194
	s_nop 1
	v_permlane32_swap_b32_e32 v194, v195
	v_add_f32_e32 v194, v194, v195
	s_mov_b64 s[74:75], exec
	s_and_b64 exec, exec, s[68:69]
	global_atomic_add_f32 v133, v194, s[38:39] offset:8
	s_mov_b64 exec, s[74:75]
	s_branch .LBB0_1251
.Lepi_vupt:
	s_lshl_b32 s9, s9, 8
	s_add_i32 s9, s9, s60
	s_lshl_b32 s78, s8, 8
	s_or_b32 s78, s78, s26
	s_lshl_b32 s8, s78, 2
	s_add_u32 s74, s36, s8
	s_addc_u32 s75, s37, 0
	s_add_u32 s74, s74, 0x1140000
	s_addc_u32 s75, s75, 0
	v_lshlrev_b32_e32 v132, 2, v176
	global_load_dwordx4 v[152:155], v132, s[74:75] offset:0
	global_load_dwordx4 v[156:159], v132, s[74:75] offset:16
	global_load_dwordx4 v[160:163], v132, s[74:75] offset:512
	global_load_dwordx4 v[164:167], v132, s[74:75] offset:528
	s_lshr_b32 s8, s78, 6
	s_lshl_b32 s8, s8, 17
	s_lshl_b32 s41, s9, 7
	s_add_i32 s8, s8, s41
	s_and_b32 s41, s78, 63
	s_lshl_b32 s41, s41, 1
	s_add_i32 s8, s8, s41
	s_add_u32 s46, s36, s8
	s_addc_u32 s47, s37, 0
	s_add_u32 s46, s46, 0xf600000
	s_addc_u32 s47, s47, 0
	v_lshlrev_b32_e32 v130, 7, v1
	v_lshl_add_u32 v130, v176, 1, v130
	v_add_u32_e32 v131, 0x40000, v130
	s_waitcnt vmcnt(0)
	v_fmamk_f32 v152, v152, 0x3c000000, v207
	v_fmamk_f32 v153, v153, 0x3c000000, v207
	v_fmamk_f32 v154, v154, 0x3c000000, v207
	v_fmamk_f32 v155, v155, 0x3c000000, v207
	v_fmamk_f32 v156, v156, 0x3c000000, v207
	v_fmamk_f32 v157, v157, 0x3c000000, v207
	v_fmamk_f32 v158, v158, 0x3c000000, v207
	v_fmamk_f32 v159, v159, 0x3c000000, v207
	v_fmamk_f32 v160, v160, 0x3c000000, v207
	v_fmamk_f32 v161, v161, 0x3c000000, v207
	v_fmamk_f32 v162, v162, 0x3c000000, v207
	v_fmamk_f32 v163, v163, 0x3c000000, v207
	v_fmamk_f32 v164, v164, 0x3c000000, v207
	v_fmamk_f32 v165, v165, 0x3c000000, v207
	v_fmamk_f32 v166, v166, 0x3c000000, v207
	v_fmamk_f32 v167, v167, 0x3c000000, v207
	v_rsq_f32_e32 v152, v152
	v_rsq_f32_e32 v153, v153
	v_rsq_f32_e32 v154, v154
	v_rsq_f32_e32 v155, v155
	v_rsq_f32_e32 v156, v156
	v_rsq_f32_e32 v157, v157
	v_rsq_f32_e32 v158, v158
	v_rsq_f32_e32 v159, v159
	v_rsq_f32_e32 v160, v160
	v_rsq_f32_e32 v161, v161
	v_rsq_f32_e32 v162, v162
	v_rsq_f32_e32 v163, v163
	v_rsq_f32_e32 v164, v164
	v_rsq_f32_e32 v165, v165
	v_rsq_f32_e32 v166, v166
	v_rsq_f32_e32 v167, v167
	v_pk_mul_f32 v[168:169], v[126:127], v[152:153]
	v_pk_mul_f32 v[170:171], v[128:129], v[154:155]
	v_pk_mul_f32 v[172:173], v[122:123], v[156:157]
	v_pk_mul_f32 v[174:175], v[124:125], v[158:159]
	v_cvt_pk_bf16_f32 v134, v168, v169
	v_cvt_pk_bf16_f32 v135, v170, v171
	v_cvt_pk_bf16_f32 v136, v172, v173
	v_cvt_pk_bf16_f32 v137, v174, v175
	global_store_dwordx4 v130, v[134:137], s[46:47]
	v_pk_mul_f32 v[180:181], v[118:119], v[160:161]
	v_pk_mul_f32 v[182:183], v[120:121], v[162:163]
	v_pk_mul_f32 v[184:185], v[114:115], v[164:165]
	v_pk_mul_f32 v[186:187], v[116:117], v[166:167]
	v_cvt_pk_bf16_f32 v188, v180, v181
	v_cvt_pk_bf16_f32 v189, v182, v183
	v_cvt_pk_bf16_f32 v190, v184, v185
	v_cvt_pk_bf16_f32 v191, v186, v187
	global_store_dwordx4 v131, v[188:191], s[46:47]
	v_pk_mul_f32 v[168:169], v[110:111], v[152:153]
	v_pk_mul_f32 v[170:171], v[112:113], v[154:155]
	v_pk_mul_f32 v[172:173], v[106:107], v[156:157]
	v_pk_mul_f32 v[174:175], v[108:109], v[158:159]
	v_cvt_pk_bf16_f32 v134, v168, v169
	v_cvt_pk_bf16_f32 v135, v170, v171
	v_cvt_pk_bf16_f32 v136, v172, v173
	v_cvt_pk_bf16_f32 v137, v174, v175
	s_add_u32 s46, s46, 0x800
	s_addc_u32 s47, s47, 0
	global_store_dwordx4 v130, v[134:137], s[46:47]
	v_pk_mul_f32 v[180:181], v[102:103], v[160:161]
	v_pk_mul_f32 v[182:183], v[104:105], v[162:163]
	v_pk_mul_f32 v[184:185], v[98:99], v[164:165]
	v_pk_mul_f32 v[186:187], v[100:101], v[166:167]
	v_cvt_pk_bf16_f32 v188, v180, v181
	v_cvt_pk_bf16_f32 v189, v182, v183
	v_cvt_pk_bf16_f32 v190, v184, v185
	v_cvt_pk_bf16_f32 v191, v186, v187
	global_store_dwordx4 v131, v[188:191], s[46:47]
	v_pk_mul_f32 v[168:169], v[94:95], v[152:153]
	v_pk_mul_f32 v[170:171], v[96:97], v[154:155]
	v_pk_mul_f32 v[172:173], v[90:91], v[156:157]
	v_pk_mul_f32 v[174:175], v[92:93], v[158:159]
	v_cvt_pk_bf16_f32 v134, v168, v169
	v_cvt_pk_bf16_f32 v135, v170, v171
	v_cvt_pk_bf16_f32 v136, v172, v173
	v_cvt_pk_bf16_f32 v137, v174, v175
	s_add_u32 s46, s46, 0x800
	s_addc_u32 s47, s47, 0
	global_store_dwordx4 v130, v[134:137], s[46:47]
	v_pk_mul_f32 v[180:181], v[86:87], v[160:161]
	v_pk_mul_f32 v[182:183], v[88:89], v[162:163]
	v_pk_mul_f32 v[184:185], v[82:83], v[164:165]
	v_pk_mul_f32 v[186:187], v[84:85], v[166:167]
	v_cvt_pk_bf16_f32 v188, v180, v181
	v_cvt_pk_bf16_f32 v189, v182, v183
	v_cvt_pk_bf16_f32 v190, v184, v185
	v_cvt_pk_bf16_f32 v191, v186, v187
	global_store_dwordx4 v131, v[188:191], s[46:47]
	v_pk_mul_f32 v[168:169], v[78:79], v[152:153]
	v_pk_mul_f32 v[170:171], v[80:81], v[154:155]
	v_pk_mul_f32 v[172:173], v[74:75], v[156:157]
	v_pk_mul_f32 v[174:175], v[76:77], v[158:159]
	v_cvt_pk_bf16_f32 v134, v168, v169
	v_cvt_pk_bf16_f32 v135, v170, v171
	v_cvt_pk_bf16_f32 v136, v172, v173
	v_cvt_pk_bf16_f32 v137, v174, v175
	s_add_u32 s46, s46, 0x800
	s_addc_u32 s47, s47, 0
	global_store_dwordx4 v130, v[134:137], s[46:47]
	v_pk_mul_f32 v[180:181], v[70:71], v[160:161]
	v_pk_mul_f32 v[182:183], v[72:73], v[162:163]
	v_pk_mul_f32 v[184:185], v[66:67], v[164:165]
	v_pk_mul_f32 v[186:187], v[68:69], v[166:167]
	v_cvt_pk_bf16_f32 v188, v180, v181
	v_cvt_pk_bf16_f32 v189, v182, v183
	v_cvt_pk_bf16_f32 v190, v184, v185
	v_cvt_pk_bf16_f32 v191, v186, v187
	global_store_dwordx4 v131, v[188:191], s[46:47]
	v_pk_mul_f32 v[168:169], v[62:63], v[152:153]
	v_pk_mul_f32 v[170:171], v[64:65], v[154:155]
	v_pk_mul_f32 v[172:173], v[58:59], v[156:157]
	v_pk_mul_f32 v[174:175], v[60:61], v[158:159]
	v_cvt_pk_bf16_f32 v134, v168, v169
	v_cvt_pk_bf16_f32 v135, v170, v171
	v_cvt_pk_bf16_f32 v136, v172, v173
	v_cvt_pk_bf16_f32 v137, v174, v175
	s_add_u32 s46, s46, 0x2800
	s_addc_u32 s47, s47, 0
	global_store_dwordx4 v130, v[134:137], s[46:47]
	v_pk_mul_f32 v[180:181], v[54:55], v[160:161]
	v_pk_mul_f32 v[182:183], v[56:57], v[162:163]
	v_pk_mul_f32 v[184:185], v[50:51], v[164:165]
	v_pk_mul_f32 v[186:187], v[52:53], v[166:167]
	v_cvt_pk_bf16_f32 v188, v180, v181
	v_cvt_pk_bf16_f32 v189, v182, v183
	v_cvt_pk_bf16_f32 v190, v184, v185
	v_cvt_pk_bf16_f32 v191, v186, v187
	global_store_dwordx4 v131, v[188:191], s[46:47]
	v_pk_mul_f32 v[168:169], v[46:47], v[152:153]
	v_pk_mul_f32 v[170:171], v[48:49], v[154:155]
	v_pk_mul_f32 v[172:173], v[42:43], v[156:157]
	v_pk_mul_f32 v[174:175], v[44:45], v[158:159]
	v_cvt_pk_bf16_f32 v134, v168, v169
	v_cvt_pk_bf16_f32 v135, v170, v171
	v_cvt_pk_bf16_f32 v136, v172, v173
	v_cvt_pk_bf16_f32 v137, v174, v175
	s_add_u32 s46, s46, 0x800
	s_addc_u32 s47, s47, 0
	global_store_dwordx4 v130, v[134:137], s[46:47]
	v_pk_mul_f32 v[180:181], v[38:39], v[160:161]
	v_pk_mul_f32 v[182:183], v[40:41], v[162:163]
	v_pk_mul_f32 v[184:185], v[34:35], v[164:165]
	v_pk_mul_f32 v[186:187], v[36:37], v[166:167]
	v_cvt_pk_bf16_f32 v188, v180, v181
	v_cvt_pk_bf16_f32 v189, v182, v183
	v_cvt_pk_bf16_f32 v190, v184, v185
	v_cvt_pk_bf16_f32 v191, v186, v187
	global_store_dwordx4 v131, v[188:191], s[46:47]
	v_pk_mul_f32 v[168:169], v[30:31], v[152:153]
	v_pk_mul_f32 v[170:171], v[32:33], v[154:155]
	v_pk_mul_f32 v[172:173], v[26:27], v[156:157]
	v_pk_mul_f32 v[174:175], v[28:29], v[158:159]
	v_cvt_pk_bf16_f32 v134, v168, v169
	v_cvt_pk_bf16_f32 v135, v170, v171
	v_cvt_pk_bf16_f32 v136, v172, v173
	v_cvt_pk_bf16_f32 v137, v174, v175
	s_add_u32 s46, s46, 0x800
	s_addc_u32 s47, s47, 0
	global_store_dwordx4 v130, v[134:137], s[46:47]
	v_pk_mul_f32 v[180:181], v[22:23], v[160:161]
	v_pk_mul_f32 v[182:183], v[24:25], v[162:163]
	v_pk_mul_f32 v[184:185], v[18:19], v[164:165]
	v_pk_mul_f32 v[186:187], v[20:21], v[166:167]
	v_cvt_pk_bf16_f32 v188, v180, v181
	v_cvt_pk_bf16_f32 v189, v182, v183
	v_cvt_pk_bf16_f32 v190, v184, v185
	v_cvt_pk_bf16_f32 v191, v186, v187
	global_store_dwordx4 v131, v[188:191], s[46:47]
	v_pk_mul_f32 v[168:169], v[14:15], v[152:153]
	v_pk_mul_f32 v[170:171], v[16:17], v[154:155]
	v_pk_mul_f32 v[172:173], v[10:11], v[156:157]
	v_pk_mul_f32 v[174:175], v[12:13], v[158:159]
	v_cvt_pk_bf16_f32 v134, v168, v169
	v_cvt_pk_bf16_f32 v135, v170, v171
	v_cvt_pk_bf16_f32 v136, v172, v173
	v_cvt_pk_bf16_f32 v137, v174, v175
	s_add_u32 s46, s46, 0x800
	s_addc_u32 s47, s47, 0
	global_store_dwordx4 v130, v[134:137], s[46:47]
	v_pk_mul_f32 v[180:181], v[6:7], v[160:161]
	v_pk_mul_f32 v[182:183], v[8:9], v[162:163]
	v_pk_mul_f32 v[184:185], v[2:3], v[164:165]
	v_pk_mul_f32 v[186:187], v[4:5], v[166:167]
	v_cvt_pk_bf16_f32 v188, v180, v181
	v_cvt_pk_bf16_f32 v189, v182, v183
	v_cvt_pk_bf16_f32 v190, v184, v185
	v_cvt_pk_bf16_f32 v191, v186, v187
	global_store_dwordx4 v131, v[188:191], s[46:47]
	s_branch .LBB0_1251
